# merge-hook early wait fixed, ffn_in unit-header vmcnt(0) removed, attention loops: removed compiler vmcnt(0) before V tr-reads (LDS-DMA ring stays 4 deep)
# speedup vs baseline: 1.0025x; 1.0025x over previous
; #define LAS __attribute__((address_space(3)))
; #define MFMA32(a, b, c) __builtin_amdgcn_mfma_f32_32x32x16_bf16((a), (b), (c), 0, 0, 0)
; #define WG_BAR() do { asm volatile("s_waitcnt lgkmcnt(0)" ::: "memory"); __builtin_amdgcn_s_barrier(); asm volatile("" ::: "memory"); } while (0)
; #define ATT_DMA(t) do { const int t_ = (t) < NS ? (t) : NS - 1; const size_t ro_ = (size_t)TILE_ROW(t_) * ZC; LAS unsigned char* d_ = dk0 + ((t) % ATT_NB) * KV_BUF; \
;         __builtin_amdgcn_global_load_lds((const unsigned*)(gk + ro_), (LAS unsigned*)d_, 16, 0, 0); __builtin_amdgcn_global_load_lds((const unsigned*)(gv + ro_), (LAS unsigned*)(d_ + KV_TILE), 16, 0, 0); } while (0)
; template <class ScoreFn>
; __device__ __forceinline__ void attn_step(AttnState& st, const bf16x8 (&qf)[4], LAS unsigned char* kb, LAS unsigned char* vb, int lane, const ScoreFn& sf) {
;     const int r = lane & 31, h = lane >> 5;
;     f32x16 s0, s1;
; #pragma unroll
;     for (int i = 0; i < 16; ++i) { s0[i] = 0.f; s1[i] = 0.f; }
;     LAS unsigned char* kp = kb + r * KVP; const int kx = (h ^ (r & 7)) << 4;
; #pragma unroll
;     for (int ds = 0; ds < 4; ++ds) {
;         const bf16x8 k0 = *(const LAS bf16x8*)(kp + (kx ^ (ds << 5))), k1 = *(const LAS bf16x8*)(kp + 32 * KVP + (kx ^ (ds << 5)));
;         s0 = MFMA32(k0, qf[ds], s0); s1 = MFMA32(k1, qf[ds], s1);
;     }
;     float mt = NEG_BIG;
;     __builtin_amdgcn_sched_barrier(0);
; #pragma unroll
;     for (int i = 0; i < 16; ++i) { s0[i] = sf(s0[i], (i & 3) + 8 * (i >> 2), h, r); mt = fmaxf(mt, s0[i]); if ((i & 7) == 7) __builtin_amdgcn_sched_barrier(0); }
; #pragma unroll
;     for (int i = 0; i < 16; ++i) { s1[i] = sf(s1[i], 32 + (i & 3) + 8 * (i >> 2), h, r); mt = fmaxf(mt, s1[i]); if ((i & 7) == 7) __builtin_amdgcn_sched_barrier(0); }
;     mt = fmaxf(mt, __shfl_xor(mt, 32));
; template <bool ISB>
; __device__ __forceinline__ void attn_wg_item(Frame& F, int l, int idx) {
;     ...
;     for (int s = 0; s < NS; ++s) {
;         ATT_DMA(s + ATT_D);
;         asm volatile("s_waitcnt vmcnt(8)" ::: "memory");
;         WG_BAR();
;         LAS unsigned char* cur = ring + (s % ATT_NB) * KV_BUF;
;         if (s >= nloc) { ScorePlain sf; attn_step(st, qf, cur, cur + KV_TILE, lane, sf); }
.LBB0_581:
	s_mul_hi_u32 s1, s16, 0xaaaaaaab
	s_mul_hi_u32 s2, s13, 0xaaaaaaab
	s_lshr_b32 s1, s1, 2
	s_lshr_b32 s2, s2, 2
	s_mul_i32 s1, s1, 0x18000
	s_mul_i32 s2, s2, 0x18000
	v_readlane_b32 s3, v253, 15
	v_subrev_u32_e32 v6, s1, v88
	v_subrev_u32_e32 v7, s1, v90
	v_subrev_u32_e32 v8, s1, v91
	v_subrev_u32_e32 v9, s1, v92
	v_subrev_u32_e32 v10, s1, v93
	v_subrev_u32_e32 v11, s1, v94
	v_subrev_u32_e32 v12, s1, v95
	v_subrev_u32_e32 v13, s1, v96
	v_subrev_u32_e32 v14, s1, v97
	v_subrev_u32_e32 v15, s1, v98
	v_subrev_u32_e32 v16, s1, v99
	v_subrev_u32_e32 v17, s1, v100
	v_subrev_u32_e32 v20, s1, v101
	v_subrev_u32_e32 v21, s1, v102
	v_subrev_u32_e32 v22, s1, v103
	v_subrev_u32_e32 v23, s1, v104
	v_subrev_u32_e32 v128, s1, v105
	s_sub_i32 s8, s3, s2
	v_subrev_u32_e32 v130, s1, v106
	v_subrev_u32_e32 v131, s1, v107
	v_subrev_u32_e32 v132, s1, v108
	s_add_i32 s1, s16, 4
	s_cmp_lt_i32 s16, s11
	s_cselect_b64 s[2:3], -1, 0
	s_and_b64 vcc, s[2:3], exec
	s_cselect_b32 s1, s1, s12
	s_cmp_lt_i32 s1, s11
	s_cselect_b32 s2, 0, s11
	s_cselect_b32 s3, s10, 0x2000
	s_sub_i32 s1, s1, s2
	s_lshl_b32 s1, s1, 6
	s_add_i32 s1, s1, s3
	s_add_i32 s2, s15, s8
	v_mov_b32_e32 v84, v2
	v_mov_b32_e32 v85, v3
	s_add_i32 s8, s2, 0
	v_mad_i64_i32 v[2:3], s[2:3], s1, v249, v[50:51]
	s_add_i32 m0, s8, 0x10000
	v_lshl_add_u64 v[4:5], v[2:3], 0, s[18:19]
	global_load_lds_dwordx4 v[4:5], off
	v_lshl_add_u64 v[2:3], v[2:3], 0, s[20:21]
	s_add_i32 m0, s8, 0x12000
	v_mov_b32_e32 v82, v18
	global_load_lds_dwordx4 v[2:3], off
	s_waitcnt vmcnt(8)
	s_waitcnt lgkmcnt(0)
	s_barrier
	v_mov_b32_e32 v83, v19
	s_mov_b64 s[8:9], -1
	v_add3_u32 v126, s15, v23, v89
	v_add3_u32 v125, s15, v13, v89
	v_add3_u32 v127, s15, v22, v89
	v_add3_u32 v124, s15, v12, v89
	v_add3_u32 v122, s15, v21, v89
	v_add3_u32 v123, s15, v20, v89
	v_add3_u32 v119, s15, v11, v89
	v_add3_u32 v120, s15, v10, v89
	v_add3_u32 v117, s15, v17, v89
	v_add3_u32 v118, s15, v16, v89
	v_add3_u32 v115, s15, v9, v89
	v_add3_u32 v116, s15, v8, v89
	v_add3_u32 v113, s15, v15, v89
	v_add3_u32 v114, s15, v14, v89
	v_add3_u32 v111, s15, v7, v89
	v_add3_u32 v112, s15, v6, v89
	s_cbranch_vccnz .LBB0_583
	s_add_i32 s1, s15, 0
	v_add_u32_e32 v6, s1, v132
	ds_read_b128 v[2:5], v6
	ds_read_b128 v[18:21], v6 offset:4096
	v_add_u32_e32 v26, s1, v131
	ds_read_b128 v[22:25], v26
	ds_read_b128 v[134:137], v26 offset:4096
	v_add_u32_e32 v27, s1, v130
	v_add_u32_e32 v26, s1, v128
	s_waitcnt lgkmcnt(0)
	v_mfma_f32_32x32x16_bf16 v[2:17], v[2:5], v[34:37], 0
	ds_read_b128 v[138:141], v27 offset:4096
	v_mfma_f32_32x32x16_bf16 v[2:17], v[22:25], v[38:41], v[2:17]
	ds_read_b128 v[22:25], v27
	s_waitcnt lgkmcnt(0)
	v_mfma_f32_32x32x16_bf16 v[2:17], v[22:25], v[42:45], v[2:17]
	ds_read_b128 v[22:25], v26
	ds_read_b128 v[142:145], v26 offset:4096
	s_waitcnt lgkmcnt(0)
	v_mfma_f32_32x32x16_bf16 v[2:17], v[22:25], v[46:49], v[2:17]
	v_mfma_f32_32x32x16_bf16 v[18:33], v[18:21], v[34:37], 0
	v_mfma_f32_32x32x16_bf16 v[18:33], v[134:137], v[38:41], v[18:33]
	v_mfma_f32_32x32x16_bf16 v[18:33], v[138:141], v[42:45], v[18:33]
	v_mfma_f32_32x32x16_bf16 v[18:33], v[142:145], v[46:49], v[18:33]
	s_nop 7
	v_mul_f32_e32 v66, 0x3e38aa3b, v2
	v_mul_f32_e32 v121, 0x3e38aa3b, v3
	s_mov_b32 s1, 0xf149f2ca
	v_max3_f32 v66, v66, s1, v121
	v_mul_f32_e32 v121, 0x3e38aa3b, v4
	v_mul_f32_e32 v129, 0x3e38aa3b, v5
	v_max3_f32 v66, v66, v121, v129
	v_mul_f32_e32 v121, 0x3e38aa3b, v6
	v_mul_f32_e32 v129, 0x3e38aa3b, v7
	v_max3_f32 v66, v66, v121, v129
	v_mul_f32_e32 v121, 0x3e38aa3b, v8
	v_mul_f32_e32 v129, 0x3e38aa3b, v9
	v_max3_f32 v66, v66, v121, v129
	v_mul_f32_e32 v121, 0x3e38aa3b, v10
	v_mul_f32_e32 v129, 0x3e38aa3b, v11
	v_max3_f32 v66, v66, v121, v129
	v_mul_f32_e32 v121, 0x3e38aa3b, v12
	v_mul_f32_e32 v129, 0x3e38aa3b, v13
	v_max3_f32 v66, v66, v121, v129
	v_mul_f32_e32 v121, 0x3e38aa3b, v14
	v_mul_f32_e32 v129, 0x3e38aa3b, v15
	v_max3_f32 v66, v66, v121, v129
	v_mul_f32_e32 v121, 0x3e38aa3b, v16
	v_mul_f32_e32 v129, 0x3e38aa3b, v17
	v_max3_f32 v66, v66, v121, v129
	v_mul_f32_e32 v121, 0x3e38aa3b, v18
	v_mul_f32_e32 v129, 0x3e38aa3b, v19
	v_max3_f32 v66, v66, v121, v129
	v_mul_f32_e32 v121, 0x3e38aa3b, v20
	v_mul_f32_e32 v129, 0x3e38aa3b, v21
	v_max3_f32 v66, v66, v121, v129
	v_mul_f32_e32 v121, 0x3e38aa3b, v22
	v_mul_f32_e32 v129, 0x3e38aa3b, v23
	v_max3_f32 v66, v66, v121, v129
	v_mul_f32_e32 v121, 0x3e38aa3b, v24
	v_mul_f32_e32 v129, 0x3e38aa3b, v25
	v_max3_f32 v66, v66, v121, v129
	v_mul_f32_e32 v121, 0x3e38aa3b, v26
	v_mul_f32_e32 v129, 0x3e38aa3b, v27
	v_max3_f32 v66, v66, v121, v129
	v_mul_f32_e32 v121, 0x3e38aa3b, v28
	v_mul_f32_e32 v129, 0x3e38aa3b, v29
	v_max3_f32 v66, v66, v121, v129
	v_mul_f32_e32 v121, 0x3e38aa3b, v30
	v_mul_f32_e32 v129, 0x3e38aa3b, v31
	v_max3_f32 v66, v66, v121, v129
	v_mul_f32_e32 v121, 0x3e38aa3b, v32
	v_mul_f32_e32 v129, 0x3e38aa3b, v33
	v_cmp_lt_i32_e32 vcc, v242, v241
	v_max3_f32 v66, v66, v121, v129
	s_nop 0
	v_cndmask_b32_e32 v121, v240, v242, vcc
	v_lshlrev_b32_e32 v121, 2, v121
	ds_bpermute_b32 v121, v121, v66
	s_waitcnt lgkmcnt(0)
; #define LAS __attribute__((address_space(3)))
; #define MFMA32(a, b, c) __builtin_amdgcn_mfma_f32_32x32x16_bf16((a), (b), (c), 0, 0, 0)
; __device__ __forceinline__ s16x4 tr_read(LAS unsigned char* p) { return __builtin_bit_cast(s16x4, __builtin_amdgcn_ds_read_tr16_b64_v4i16((LAS v4i16_t*)p)); }
; template <class ScoreFn>
; __device__ __forceinline__ void attn_step(AttnState& st, const bf16x8 (&qf)[4], LAS unsigned char* kb, LAS unsigned char* vb, int lane, const ScoreFn& sf) {
;     ...
;     const float mn = fmaxf(st.m, mt), alpha = __builtin_amdgcn_exp2f(st.m - mn);
;     float ps = 0.f;
; #pragma unroll
;     for (int i = 0; i < 16; ++i) { s0[i] = __builtin_amdgcn_exp2f(s0[i] - mn); s1[i] = __builtin_amdgcn_exp2f(s1[i] - mn); ps += s0[i] + s1[i]; }
;     st.l = st.l * alpha + ps; st.m = mn;
; #pragma unroll
;     for (int i = 0; i < 16; ++i) { st.o0[i] *= alpha; st.o1[i] *= alpha; }
;     __builtin_amdgcn_sched_barrier(0);
;     v4u pw[4];
;     pw[0].x = cvtpk(s0[0], s0[1]); pw[0].y = cvtpk(s0[2], s0[3]); pw[0].z = cvtpk(s0[4], s0[5]); pw[0].w = cvtpk(s0[6], s0[7]);
;     pw[1].x = cvtpk(s0[8], s0[9]); pw[1].y = cvtpk(s0[10], s0[11]); pw[1].z = cvtpk(s0[12], s0[13]); pw[1].w = cvtpk(s0[14], s0[15]);
;     pw[2].x = cvtpk(s1[0], s1[1]); pw[2].y = cvtpk(s1[2], s1[3]); pw[2].z = cvtpk(s1[4], s1[5]); pw[2].w = cvtpk(s1[6], s1[7]);
;     pw[3].x = cvtpk(s1[8], s1[9]); pw[3].y = cvtpk(s1[10], s1[11]); pw[3].z = cvtpk(s1[12], s1[13]); pw[3].w = cvtpk(s1[14], s1[15]);
;     const int i16 = lane & 15, q = i16 >> 2, p = i16 & 3, dhalf = (lane >> 4) & 1;
;     LAS unsigned char* vrow = vb + (4 * h + q) * KVP + (p & 1) * 8;
;     LAS unsigned char* vp0 = vrow + (((2 * dhalf + (p >> 1)) ^ (4 * h + q)) << 4); LAS unsigned char* vp1 = vrow + (((4 + 2 * dhalf + (p >> 1)) ^ (4 * h + q)) << 4);
; #pragma unroll
;     for (int ks = 0; ks < 4; ++ks) {
;         const s16x4 l0 = tr_read(vp0 + (16 * ks) * KVP), h0 = tr_read(vp0 + (16 * ks + 8) * KVP);
;         const s16x4 l1 = tr_read(vp1 + (16 * ks) * KVP), h1 = tr_read(vp1 + (16 * ks + 8) * KVP);
;         const bf16x8 v0 = (bf16x8){l0[0], l0[1], l0[2], l0[3], h0[0], h0[1], h0[2], h0[3]};
;         const bf16x8 v1 = (bf16x8){l1[0], l1[1], l1[2], l1[3], h1[0], h1[1], h1[2], h1[3]};
;         const bf16x8 pf = __builtin_bit_cast(bf16x8, pw[ks]);
;         st.o0 = MFMA32(v0, pf, st.o0); st.o1 = MFMA32(v1, pf, st.o1);
;     }
	v_max3_f32 v121, v110, v66, v121
	v_fma_f32 v2, v2, s0, -v121
	v_exp_f32_e32 v133, v2
	v_fma_f32 v2, v18, s0, -v121
	v_exp_f32_e32 v165, v2
	v_fma_f32 v2, v3, s0, -v121
	v_exp_f32_e32 v66, v2
	v_fma_f32 v2, v19, s0, -v121
	v_exp_f32_e32 v142, v2
	v_add_f32_e32 v143, v165, v133
	v_pk_add_f32 v[2:3], v[142:143], v[66:67]
	s_nop 0
	v_pk_add_f32 v[136:137], v[2:3], v[2:3] op_sel_hi:[0,1]
	v_fma_f32 v2, v4, s0, -v121
	v_exp_f32_e32 v135, v2
	v_fma_f32 v2, v20, s0, -v121
	v_exp_f32_e32 v143, v2
	v_fma_f32 v2, v5, s0, -v121
	v_exp_f32_e32 v136, v2
	v_fma_f32 v2, v21, s0, -v121
	v_exp_f32_e32 v144, v2
	v_add_f32_e32 v145, v143, v135
	v_pk_add_f32 v[2:3], v[144:145], v[136:137]
	s_nop 0
	v_pk_add_f32 v[138:139], v[2:3], v[2:3] op_sel_hi:[0,1]
	v_fma_f32 v2, v6, s0, -v121
	v_exp_f32_e32 v137, v2
	v_fma_f32 v2, v22, s0, -v121
	v_exp_f32_e32 v145, v2
	v_fma_f32 v2, v7, s0, -v121
	v_exp_f32_e32 v138, v2
	v_fma_f32 v2, v23, s0, -v121
	v_exp_f32_e32 v146, v2
	v_add_f32_e32 v147, v145, v137
	v_pk_add_f32 v[2:3], v[146:147], v[138:139]
	s_nop 0
	v_pk_add_f32 v[140:141], v[2:3], v[2:3] op_sel_hi:[0,1]
	v_fma_f32 v2, v8, s0, -v121
	v_exp_f32_e32 v139, v2
	v_fma_f32 v2, v24, s0, -v121
	v_exp_f32_e32 v147, v2
	v_fma_f32 v2, v9, s0, -v121
	v_exp_f32_e32 v140, v2
	v_fma_f32 v2, v25, s0, -v121
	v_exp_f32_e32 v148, v2
	v_add_f32_e32 v149, v147, v139
	v_pk_add_f32 v[2:3], v[148:149], v[140:141]
	s_nop 0
	v_pk_add_f32 v[150:151], v[2:3], v[2:3] op_sel_hi:[0,1]
	v_fma_f32 v2, v10, s0, -v121
	v_exp_f32_e32 v141, v2
	v_fma_f32 v2, v26, s0, -v121
	v_exp_f32_e32 v149, v2
	v_fma_f32 v2, v11, s0, -v121
	v_exp_f32_e32 v150, v2
	v_fma_f32 v2, v27, s0, -v121
	v_exp_f32_e32 v152, v2
	v_add_f32_e32 v153, v149, v141
	v_pk_add_f32 v[2:3], v[152:153], v[150:151]
	s_nop 0
	v_pk_add_f32 v[154:155], v[2:3], v[2:3] op_sel_hi:[0,1]
	v_fma_f32 v2, v12, s0, -v121
	v_exp_f32_e32 v151, v2
	v_fma_f32 v2, v28, s0, -v121
	v_exp_f32_e32 v153, v2
	v_fma_f32 v2, v13, s0, -v121
	v_exp_f32_e32 v154, v2
	v_fma_f32 v2, v29, s0, -v121
	v_exp_f32_e32 v156, v2
	v_add_f32_e32 v157, v153, v151
	v_pk_add_f32 v[2:3], v[156:157], v[154:155]
	s_nop 0
	v_pk_add_f32 v[158:159], v[2:3], v[2:3] op_sel_hi:[0,1]
	v_fma_f32 v2, v14, s0, -v121
	v_exp_f32_e32 v155, v2
	v_fma_f32 v2, v30, s0, -v121
	v_exp_f32_e32 v157, v2
	v_fma_f32 v2, v15, s0, -v121
	v_exp_f32_e32 v158, v2
	v_fma_f32 v2, v31, s0, -v121
	v_exp_f32_e32 v160, v2
	v_add_f32_e32 v161, v157, v155
	v_pk_add_f32 v[2:3], v[160:161], v[158:159]
	s_nop 0
	v_pk_add_f32 v[162:163], v[2:3], v[2:3] op_sel_hi:[0,1]
	v_fma_f32 v2, v16, s0, -v121
	v_exp_f32_e32 v159, v2
	v_fma_f32 v2, v32, s0, -v121
	v_exp_f32_e32 v161, v2
	v_fma_f32 v2, v17, s0, -v121
	v_exp_f32_e32 v162, v2
	v_fma_f32 v2, v33, s0, -v121
	v_exp_f32_e32 v166, v2
	v_sub_f32_e32 v2, v110, v121
	v_exp_f32_e32 v18, v2
	v_add_f32_e32 v167, v161, v159
	v_pk_add_f32 v[2:3], v[166:167], v[162:163]
	v_pk_mul_f32 v[16:17], v[80:81], v[18:19] op_sel_hi:[1,0]
	v_add_f32_e32 v129, v2, v3
	v_fmac_f32_e32 v129, v109, v18
	v_pk_mul_f32 v[14:15], v[76:77], v[18:19] op_sel_hi:[1,0]
	v_pk_mul_f32 v[12:13], v[72:73], v[18:19] op_sel_hi:[1,0]
	v_pk_mul_f32 v[10:11], v[68:69], v[18:19] op_sel_hi:[1,0]
	v_pk_mul_f32 v[8:9], v[62:63], v[18:19] op_sel_hi:[1,0]
	v_pk_mul_f32 v[6:7], v[58:59], v[18:19] op_sel_hi:[1,0]
	v_pk_mul_f32 v[4:5], v[54:55], v[18:19] op_sel_hi:[1,0]
	v_pk_mul_f32 v[2:3], v[84:85], v[18:19] op_sel_hi:[1,0]
	v_pk_mul_f32 v[32:33], v[78:79], v[18:19] op_sel_hi:[1,0]
	v_pk_mul_f32 v[30:31], v[74:75], v[18:19] op_sel_hi:[1,0]
	v_pk_mul_f32 v[28:29], v[70:71], v[18:19] op_sel_hi:[1,0]
	v_pk_mul_f32 v[26:27], v[64:65], v[18:19] op_sel_hi:[1,0]
	v_pk_mul_f32 v[24:25], v[60:61], v[18:19] op_sel_hi:[1,0]
	v_pk_mul_f32 v[22:23], v[56:57], v[18:19] op_sel_hi:[1,0]
	v_pk_mul_f32 v[20:21], v[52:53], v[18:19] op_sel_hi:[1,0]
	v_pk_mul_f32 v[18:19], v[82:83], v[18:19] op_sel_hi:[1,0]
	v_cvt_pk_bf16_f32 v135, v135, v136
	v_cvt_pk_bf16_f32 v136, v137, v138
	v_cvt_pk_bf16_f32 v137, v139, v140
	v_cvt_pk_bf16_f32 v138, v141, v150
	v_cvt_pk_bf16_f32 v139, v151, v154
	v_cvt_pk_bf16_f32 v140, v155, v158
	v_cvt_pk_bf16_f32 v143, v143, v144
	v_cvt_pk_bf16_f32 v144, v145, v146
	v_cvt_pk_bf16_f32 v145, v147, v148
	v_cvt_pk_bf16_f32 v146, v149, v152
	v_cvt_pk_bf16_f32 v147, v153, v156
	v_cvt_pk_bf16_f32 v148, v157, v160
	ds_read_b64_tr_b16 v[150:151], v126
	ds_read_b64_tr_b16 v[152:153], v127
	ds_read_b64_tr_b16 v[154:155], v125
	ds_read_b64_tr_b16 v[156:157], v124
	v_cvt_pk_bf16_f32 v134, v133, v66
	v_cvt_pk_bf16_f32 v141, v159, v162
	v_cvt_pk_bf16_f32 v142, v165, v142
	s_waitcnt lgkmcnt(2)
	v_mfma_f32_32x32x16_bf16 v[2:17], v[150:153], v[134:137], v[2:17]
	v_cvt_pk_bf16_f32 v149, v161, v166
	s_mov_b64 s[8:9], 0
	s_waitcnt lgkmcnt(0)
	v_mfma_f32_32x32x16_bf16 v[18:33], v[154:157], v[134:137], v[18:33]
	ds_read_b64_tr_b16 v[134:135], v122
	ds_read_b64_tr_b16 v[136:137], v123
	ds_read_b64_tr_b16 v[150:151], v119
	ds_read_b64_tr_b16 v[152:153], v120
	s_waitcnt lgkmcnt(2)
	v_mfma_f32_32x32x16_bf16 v[2:17], v[134:137], v[138:141], v[2:17]
	s_waitcnt lgkmcnt(0)
	v_mfma_f32_32x32x16_bf16 v[18:33], v[150:153], v[138:141], v[18:33]
	ds_read_b64_tr_b16 v[134:135], v117
	ds_read_b64_tr_b16 v[136:137], v118
	ds_read_b64_tr_b16 v[138:139], v115
	ds_read_b64_tr_b16 v[140:141], v116
	s_waitcnt lgkmcnt(2)
	v_mfma_f32_32x32x16_bf16 v[2:17], v[134:137], v[142:145], v[2:17]
	s_waitcnt lgkmcnt(0)
	v_mfma_f32_32x32x16_bf16 v[18:33], v[138:141], v[142:145], v[18:33]
	ds_read_b64_tr_b16 v[134:135], v113
	ds_read_b64_tr_b16 v[136:137], v114
	ds_read_b64_tr_b16 v[138:139], v111
	ds_read_b64_tr_b16 v[140:141], v112
	s_waitcnt lgkmcnt(2)
	v_mfma_f32_32x32x16_bf16 v[2:17], v[134:137], v[146:149], v[2:17]
	s_waitcnt lgkmcnt(0)
	v_mfma_f32_32x32x16_bf16 v[18:33], v[138:141], v[146:149], v[18:33]
; #define LAS __attribute__((address_space(3)))
; #define MFMA32(a, b, c) __builtin_amdgcn_mfma_f32_32x32x16_bf16((a), (b), (c), 0, 0, 0)
; template <class ScoreFn>
; __device__ __forceinline__ void attn_step(AttnState& st, const bf16x8 (&qf)[4], LAS unsigned char* kb, LAS unsigned char* vb, int lane, const ScoreFn& sf) {
;     const int r = lane & 31, h = lane >> 5;
;     f32x16 s0, s1;
; #pragma unroll
;     for (int i = 0; i < 16; ++i) { s0[i] = 0.f; s1[i] = 0.f; }
;     LAS unsigned char* kp = kb + r * KVP; const int kx = (h ^ (r & 7)) << 4;
; #pragma unroll
;     for (int ds = 0; ds < 4; ++ds) {
;         const bf16x8 k0 = *(const LAS bf16x8*)(kp + (kx ^ (ds << 5))), k1 = *(const LAS bf16x8*)(kp + 32 * KVP + (kx ^ (ds << 5)));
;         s0 = MFMA32(k0, qf[ds], s0); s1 = MFMA32(k1, qf[ds], s1);
;     }
;     float mt = NEG_BIG;
;     __builtin_amdgcn_sched_barrier(0);
; #pragma unroll
;     for (int i = 0; i < 16; ++i) { s0[i] = sf(s0[i], (i & 3) + 8 * (i >> 2), h, r); mt = fmaxf(mt, s0[i]); if ((i & 7) == 7) __builtin_amdgcn_sched_barrier(0); }
; #pragma unroll
;     for (int i = 0; i < 16; ++i) { s1[i] = sf(s1[i], 32 + (i & 3) + 8 * (i >> 2), h, r); mt = fmaxf(mt, s1[i]); if ((i & 7) == 7) __builtin_amdgcn_sched_barrier(0); }
;     mt = fmaxf(mt, __shfl_xor(mt, 32));
.LBB0_583:
	s_andn2_b64 vcc, exec, s[8:9]
	s_cbranch_vccnz .LBB0_585
	s_add_i32 s1, s15, 0
	v_mov_b32_e32 v66, s14
	s_nop 5
	v_add_u32_e32 v6, s1, v132
	ds_read_b128 v[2:5], v6
	v_add_u32_e32 v10, s1, v131
	v_add_u32_e32 v11, s1, v130
	ds_read_b128 v[130:133], v10 offset:4096
	ds_read_b128 v[6:9], v6 offset:4096
	s_waitcnt lgkmcnt(0)
	v_mfma_f32_32x32x16_bf16 v[18:33], v[2:5], v[34:37], 0
	ds_read_b128 v[2:5], v10
	v_add_u32_e32 v10, s1, v128
	ds_read_b128 v[134:137], v11 offset:4096
	s_waitcnt lgkmcnt(0)
	v_mfma_f32_32x32x16_bf16 v[18:33], v[2:5], v[38:41], v[18:33]
	ds_read_b128 v[2:5], v11
	s_waitcnt lgkmcnt(0)
	v_mfma_f32_32x32x16_bf16 v[18:33], v[2:5], v[42:45], v[18:33]
	ds_read_b128 v[2:5], v10
	ds_read_b128 v[138:141], v10 offset:4096
	s_waitcnt lgkmcnt(0)
	v_mfma_f32_32x32x16_bf16 v[18:33], v[2:5], v[46:49], v[18:33]
	v_mfma_f32_32x32x16_bf16 v[2:17], v[6:9], v[34:37], 0
	v_mfma_f32_32x32x16_bf16 v[2:17], v[130:133], v[38:41], v[2:17]
	v_mfma_f32_32x32x16_bf16 v[2:17], v[134:137], v[42:45], v[2:17]
	v_mfma_f32_32x32x16_bf16 v[2:17], v[138:141], v[46:49], v[2:17]
	v_add_u32_e32 v121, v86, v66
	s_nop 6
	v_mul_f32_e32 v18, 0x3e38aa3b, v18
	v_cmp_gt_u32_e32 vcc, s17, v121
	v_add_u32_e32 v128, 1, v121
	v_mul_f32_e32 v19, 0x3e38aa3b, v19
	v_cndmask_b32_e32 v18, v250, v18, vcc
	v_cmp_gt_u32_e32 vcc, s17, v128
	v_add_u32_e32 v129, 2, v121
	v_mul_f32_e32 v20, 0x3e38aa3b, v20
	v_cndmask_b32_e32 v19, v250, v19, vcc
	v_cmp_gt_u32_e32 vcc, s17, v129
	v_add_u32_e32 v129, 3, v121
	v_mul_f32_e32 v21, 0x3e38aa3b, v21
	v_cndmask_b32_e32 v20, v250, v20, vcc
	v_cmp_gt_u32_e32 vcc, s17, v129
	v_add_u32_e32 v129, 8, v121
	v_mul_f32_e32 v22, 0x3e38aa3b, v22
	v_cndmask_b32_e32 v21, v250, v21, vcc
	v_cmp_gt_u32_e32 vcc, s17, v129
	v_add_u32_e32 v129, 9, v121
	v_mul_f32_e32 v23, 0x3e38aa3b, v23
	v_cndmask_b32_e32 v22, v250, v22, vcc
	v_cmp_gt_u32_e32 vcc, s17, v129
	v_add_u32_e32 v129, 10, v121
	v_mul_f32_e32 v24, 0x3e38aa3b, v24
	v_cndmask_b32_e32 v23, v250, v23, vcc
	v_cmp_gt_u32_e32 vcc, s17, v129
	v_add_u32_e32 v129, 11, v121
	v_mul_f32_e32 v25, 0x3e38aa3b, v25
	v_cndmask_b32_e32 v24, v250, v24, vcc
	v_cmp_gt_u32_e32 vcc, s17, v129
	v_add_u32_e32 v129, 16, v121
	v_mul_f32_e32 v26, 0x3e38aa3b, v26
	v_cndmask_b32_e32 v25, v250, v25, vcc
	v_cmp_gt_u32_e32 vcc, s17, v129
	v_add_u32_e32 v129, 17, v121
	s_mov_b32 s1, 0xf149f2ca
	v_cndmask_b32_e32 v26, v250, v26, vcc
	v_mul_f32_e32 v27, 0x3e38aa3b, v27
	v_cmp_gt_u32_e32 vcc, s17, v129
	v_add_u32_e32 v129, 18, v121
	v_max3_f32 v128, v18, s1, v19
	v_cndmask_b32_e32 v27, v250, v27, vcc
	v_mul_f32_e32 v28, 0x3e38aa3b, v28
	v_cmp_gt_u32_e32 vcc, s17, v129
	v_add_u32_e32 v129, 19, v121
	v_max3_f32 v128, v128, v20, v21
	v_cndmask_b32_e32 v28, v250, v28, vcc
	v_mul_f32_e32 v29, 0x3e38aa3b, v29
	v_cmp_gt_u32_e32 vcc, s17, v129
	v_add_u32_e32 v129, 24, v121
	v_max3_f32 v128, v128, v22, v23
	v_cndmask_b32_e32 v29, v250, v29, vcc
	v_mul_f32_e32 v30, 0x3e38aa3b, v30
	v_cmp_gt_u32_e32 vcc, s17, v129
	v_add_u32_e32 v129, 25, v121
	v_max3_f32 v128, v128, v24, v25
	v_cndmask_b32_e32 v30, v250, v30, vcc
	v_mul_f32_e32 v31, 0x3e38aa3b, v31
	v_cmp_gt_u32_e32 vcc, s17, v129
	v_add_u32_e32 v129, 26, v121
	v_max3_f32 v128, v128, v26, v27
	v_cndmask_b32_e32 v31, v250, v31, vcc
	v_mul_f32_e32 v32, 0x3e38aa3b, v32
	v_cmp_gt_u32_e32 vcc, s17, v129
	v_add_u32_e32 v121, 27, v121
	v_max3_f32 v128, v128, v28, v29
	v_cndmask_b32_e32 v32, v250, v32, vcc
	v_mul_f32_e32 v33, 0x3e38aa3b, v33
	v_cmp_gt_u32_e32 vcc, s17, v121
	v_max3_f32 v128, v128, v30, v31
	v_add_u32_e32 v66, v87, v66
	v_cndmask_b32_e32 v33, v250, v33, vcc
	v_max3_f32 v121, v128, v32, v33
	v_mul_f32_e32 v2, 0x3e38aa3b, v2
	v_cmp_gt_u32_e32 vcc, s17, v66
	v_add_u32_e32 v128, 1, v66
	v_mul_f32_e32 v3, 0x3e38aa3b, v3
	v_cndmask_b32_e32 v2, v250, v2, vcc
	v_cmp_gt_u32_e32 vcc, s17, v128
	v_add_u32_e32 v128, 2, v66
	v_mul_f32_e32 v4, 0x3e38aa3b, v4
	v_cndmask_b32_e32 v3, v250, v3, vcc
	v_cmp_gt_u32_e32 vcc, s17, v128
	v_add_u32_e32 v128, 3, v66
	v_mul_f32_e32 v5, 0x3e38aa3b, v5
	v_cndmask_b32_e32 v4, v250, v4, vcc
	v_cmp_gt_u32_e32 vcc, s17, v128
	v_add_u32_e32 v128, 8, v66
	v_mul_f32_e32 v6, 0x3e38aa3b, v6
	v_cndmask_b32_e32 v5, v250, v5, vcc
	v_cmp_gt_u32_e32 vcc, s17, v128
	v_add_u32_e32 v128, 9, v66
	v_mul_f32_e32 v7, 0x3e38aa3b, v7
	v_cndmask_b32_e32 v6, v250, v6, vcc
	v_cmp_gt_u32_e32 vcc, s17, v128
	v_add_u32_e32 v128, 10, v66
	v_mul_f32_e32 v8, 0x3e38aa3b, v8
	v_cndmask_b32_e32 v7, v250, v7, vcc
	v_cmp_gt_u32_e32 vcc, s17, v128
	v_add_u32_e32 v128, 11, v66
	v_mul_f32_e32 v9, 0x3e38aa3b, v9
	v_cndmask_b32_e32 v8, v250, v8, vcc
	v_cmp_gt_u32_e32 vcc, s17, v128
	v_add_u32_e32 v128, 16, v66
	v_mul_f32_e32 v10, 0x3e38aa3b, v10
	v_cndmask_b32_e32 v9, v250, v9, vcc
	v_cmp_gt_u32_e32 vcc, s17, v128
	v_add_u32_e32 v128, 17, v66
	v_mul_f32_e32 v11, 0x3e38aa3b, v11
	v_cndmask_b32_e32 v10, v250, v10, vcc
	v_cmp_gt_u32_e32 vcc, s17, v128
	v_add_u32_e32 v128, 18, v66
	v_max3_f32 v121, v121, v2, v3
	v_cndmask_b32_e32 v11, v250, v11, vcc
	v_mul_f32_e32 v12, 0x3e38aa3b, v12
	v_cmp_gt_u32_e32 vcc, s17, v128
	v_add_u32_e32 v128, 19, v66
	v_max3_f32 v121, v121, v4, v5
	v_cndmask_b32_e32 v12, v250, v12, vcc
	v_mul_f32_e32 v13, 0x3e38aa3b, v13
	v_cmp_gt_u32_e32 vcc, s17, v128
	v_add_u32_e32 v128, 24, v66
	v_max3_f32 v121, v121, v6, v7
	v_cndmask_b32_e32 v13, v250, v13, vcc
	v_mul_f32_e32 v14, 0x3e38aa3b, v14
	v_cmp_gt_u32_e32 vcc, s17, v128
	v_add_u32_e32 v128, 25, v66
	v_max3_f32 v121, v121, v8, v9
	v_cndmask_b32_e32 v14, v250, v14, vcc
	v_mul_f32_e32 v15, 0x3e38aa3b, v15
	v_cmp_gt_u32_e32 vcc, s17, v128
	v_add_u32_e32 v128, 26, v66
	v_max3_f32 v121, v121, v10, v11
	v_cndmask_b32_e32 v15, v250, v15, vcc
	v_mul_f32_e32 v16, 0x3e38aa3b, v16
	v_cmp_gt_u32_e32 vcc, s17, v128
	v_add_u32_e32 v66, 27, v66
	v_max3_f32 v121, v121, v12, v13
	v_cndmask_b32_e32 v16, v250, v16, vcc
	v_mul_f32_e32 v17, 0x3e38aa3b, v17
	v_cmp_gt_u32_e32 vcc, s17, v66
	v_max3_f32 v121, v121, v14, v15
	s_nop 0
	v_cndmask_b32_e32 v17, v250, v17, vcc
	v_cmp_lt_i32_e32 vcc, v242, v241
	v_max3_f32 v66, v121, v16, v17
	s_nop 0
	v_cndmask_b32_e32 v121, v240, v242, vcc
	v_lshlrev_b32_e32 v121, 2, v121
	ds_bpermute_b32 v121, v121, v66
	s_waitcnt lgkmcnt(0)
; #define LAS __attribute__((address_space(3)))
; #define MFMA32(a, b, c) __builtin_amdgcn_mfma_f32_32x32x16_bf16((a), (b), (c), 0, 0, 0)
; __device__ __forceinline__ s16x4 tr_read(LAS unsigned char* p) { return __builtin_bit_cast(s16x4, __builtin_amdgcn_ds_read_tr16_b64_v4i16((LAS v4i16_t*)p)); }
; template <class ScoreFn>
; __device__ __forceinline__ void attn_step(AttnState& st, const bf16x8 (&qf)[4], LAS unsigned char* kb, LAS unsigned char* vb, int lane, const ScoreFn& sf) {
;     ...
;     const float mn = fmaxf(st.m, mt), alpha = __builtin_amdgcn_exp2f(st.m - mn);
;     float ps = 0.f;
; #pragma unroll
;     for (int i = 0; i < 16; ++i) { s0[i] = __builtin_amdgcn_exp2f(s0[i] - mn); s1[i] = __builtin_amdgcn_exp2f(s1[i] - mn); ps += s0[i] + s1[i]; }
;     st.l = st.l * alpha + ps; st.m = mn;
; #pragma unroll
;     for (int i = 0; i < 16; ++i) { st.o0[i] *= alpha; st.o1[i] *= alpha; }
;     __builtin_amdgcn_sched_barrier(0);
;     v4u pw[4];
;     pw[0].x = cvtpk(s0[0], s0[1]); pw[0].y = cvtpk(s0[2], s0[3]); pw[0].z = cvtpk(s0[4], s0[5]); pw[0].w = cvtpk(s0[6], s0[7]);
;     pw[1].x = cvtpk(s0[8], s0[9]); pw[1].y = cvtpk(s0[10], s0[11]); pw[1].z = cvtpk(s0[12], s0[13]); pw[1].w = cvtpk(s0[14], s0[15]);
;     pw[2].x = cvtpk(s1[0], s1[1]); pw[2].y = cvtpk(s1[2], s1[3]); pw[2].z = cvtpk(s1[4], s1[5]); pw[2].w = cvtpk(s1[6], s1[7]);
;     pw[3].x = cvtpk(s1[8], s1[9]); pw[3].y = cvtpk(s1[10], s1[11]); pw[3].z = cvtpk(s1[12], s1[13]); pw[3].w = cvtpk(s1[14], s1[15]);
;     const int i16 = lane & 15, q = i16 >> 2, p = i16 & 3, dhalf = (lane >> 4) & 1;
;     LAS unsigned char* vrow = vb + (4 * h + q) * KVP + (p & 1) * 8;
;     LAS unsigned char* vp0 = vrow + (((2 * dhalf + (p >> 1)) ^ (4 * h + q)) << 4); LAS unsigned char* vp1 = vrow + (((4 + 2 * dhalf + (p >> 1)) ^ (4 * h + q)) << 4);
; #pragma unroll
;     for (int ks = 0; ks < 4; ++ks) {
;         const s16x4 l0 = tr_read(vp0 + (16 * ks) * KVP), h0 = tr_read(vp0 + (16 * ks + 8) * KVP);
;         const s16x4 l1 = tr_read(vp1 + (16 * ks) * KVP), h1 = tr_read(vp1 + (16 * ks + 8) * KVP);
;         const bf16x8 v0 = (bf16x8){l0[0], l0[1], l0[2], l0[3], h0[0], h0[1], h0[2], h0[3]};
;         const bf16x8 v1 = (bf16x8){l1[0], l1[1], l1[2], l1[3], h1[0], h1[1], h1[2], h1[3]};
;         const bf16x8 pf = __builtin_bit_cast(bf16x8, pw[ks]);
;         st.o0 = MFMA32(v0, pf, st.o0); st.o1 = MFMA32(v1, pf, st.o1);
;     }
	v_max3_f32 v121, v110, v66, v121
	v_sub_f32_e32 v2, v2, v121
	v_sub_f32_e32 v18, v18, v121
	v_exp_f32_e32 v159, v2
	v_sub_f32_e32 v2, v19, v121
	v_exp_f32_e32 v158, v18
	v_exp_f32_e32 v66, v2
	v_sub_f32_e32 v2, v3, v121
	v_exp_f32_e32 v128, v2
	v_add_f32_e32 v129, v159, v158
	v_pk_add_f32 v[2:3], v[128:129], v[66:67]
	s_nop 0
	v_pk_add_f32 v[130:131], v[2:3], v[2:3] op_sel_hi:[0,1]
	v_sub_f32_e32 v2, v20, v121
	v_exp_f32_e32 v160, v2
	v_sub_f32_e32 v2, v4, v121
	v_exp_f32_e32 v161, v2
	v_sub_f32_e32 v2, v21, v121
	v_exp_f32_e32 v130, v2
	v_sub_f32_e32 v2, v5, v121
	v_exp_f32_e32 v132, v2
	v_add_f32_e32 v133, v161, v160
	v_pk_add_f32 v[2:3], v[132:133], v[130:131]
	s_nop 0
	v_pk_add_f32 v[134:135], v[2:3], v[2:3] op_sel_hi:[0,1]
	v_sub_f32_e32 v2, v22, v121
	v_exp_f32_e32 v131, v2
	v_sub_f32_e32 v2, v6, v121
	v_exp_f32_e32 v133, v2
	v_sub_f32_e32 v2, v23, v121
	v_exp_f32_e32 v134, v2
	v_sub_f32_e32 v2, v7, v121
	v_exp_f32_e32 v136, v2
	v_add_f32_e32 v137, v133, v131
	v_pk_add_f32 v[2:3], v[136:137], v[134:135]
	s_nop 0
	v_pk_add_f32 v[138:139], v[2:3], v[2:3] op_sel_hi:[0,1]
	v_sub_f32_e32 v2, v24, v121
	v_exp_f32_e32 v135, v2
	v_sub_f32_e32 v2, v8, v121
	v_exp_f32_e32 v137, v2
	v_sub_f32_e32 v2, v25, v121
	v_exp_f32_e32 v138, v2
	v_sub_f32_e32 v2, v9, v121
	v_exp_f32_e32 v140, v2
	v_add_f32_e32 v141, v137, v135
	v_pk_add_f32 v[2:3], v[140:141], v[138:139]
	s_nop 0
	v_pk_add_f32 v[142:143], v[2:3], v[2:3] op_sel_hi:[0,1]
	v_sub_f32_e32 v2, v26, v121
	v_exp_f32_e32 v139, v2
	v_sub_f32_e32 v2, v10, v121
	v_exp_f32_e32 v141, v2
	v_sub_f32_e32 v2, v27, v121
	v_exp_f32_e32 v142, v2
	v_sub_f32_e32 v2, v11, v121
	v_exp_f32_e32 v144, v2
	v_add_f32_e32 v145, v141, v139
	v_pk_add_f32 v[2:3], v[144:145], v[142:143]
	s_nop 0
	v_pk_add_f32 v[146:147], v[2:3], v[2:3] op_sel_hi:[0,1]
	v_sub_f32_e32 v2, v28, v121
	v_exp_f32_e32 v143, v2
	v_sub_f32_e32 v2, v12, v121
	v_exp_f32_e32 v145, v2
	v_sub_f32_e32 v2, v29, v121
	v_exp_f32_e32 v146, v2
	v_sub_f32_e32 v2, v13, v121
	v_exp_f32_e32 v148, v2
	v_add_f32_e32 v149, v145, v143
	v_pk_add_f32 v[2:3], v[148:149], v[146:147]
	s_nop 0
	v_pk_add_f32 v[150:151], v[2:3], v[2:3] op_sel_hi:[0,1]
	v_sub_f32_e32 v2, v30, v121
	v_exp_f32_e32 v147, v2
	v_sub_f32_e32 v2, v14, v121
	v_exp_f32_e32 v149, v2
	v_sub_f32_e32 v2, v31, v121
	v_exp_f32_e32 v150, v2
	v_sub_f32_e32 v2, v15, v121
	v_exp_f32_e32 v152, v2
	v_add_f32_e32 v153, v149, v147
	v_pk_add_f32 v[2:3], v[152:153], v[150:151]
	s_nop 0
	v_pk_add_f32 v[154:155], v[2:3], v[2:3] op_sel_hi:[0,1]
	v_sub_f32_e32 v2, v32, v121
	v_exp_f32_e32 v151, v2
	v_sub_f32_e32 v2, v16, v121
	v_exp_f32_e32 v153, v2
	v_sub_f32_e32 v2, v33, v121
	v_exp_f32_e32 v154, v2
	v_sub_f32_e32 v2, v17, v121
	v_exp_f32_e32 v156, v2
	v_sub_f32_e32 v2, v110, v121
	v_exp_f32_e32 v18, v2
	v_add_f32_e32 v157, v153, v151
	v_pk_add_f32 v[2:3], v[156:157], v[154:155]
	v_pk_mul_f32 v[16:17], v[80:81], v[18:19] op_sel_hi:[1,0]
	v_add_f32_e32 v129, v2, v3
	v_fmac_f32_e32 v129, v109, v18
	v_pk_mul_f32 v[14:15], v[76:77], v[18:19] op_sel_hi:[1,0]
	v_pk_mul_f32 v[12:13], v[72:73], v[18:19] op_sel_hi:[1,0]
	v_pk_mul_f32 v[10:11], v[68:69], v[18:19] op_sel_hi:[1,0]
	v_pk_mul_f32 v[8:9], v[62:63], v[18:19] op_sel_hi:[1,0]
	v_pk_mul_f32 v[6:7], v[58:59], v[18:19] op_sel_hi:[1,0]
	v_pk_mul_f32 v[4:5], v[54:55], v[18:19] op_sel_hi:[1,0]
	v_pk_mul_f32 v[2:3], v[84:85], v[18:19] op_sel_hi:[1,0]
	v_pk_mul_f32 v[32:33], v[78:79], v[18:19] op_sel_hi:[1,0]
	v_pk_mul_f32 v[30:31], v[74:75], v[18:19] op_sel_hi:[1,0]
	v_pk_mul_f32 v[28:29], v[70:71], v[18:19] op_sel_hi:[1,0]
	v_pk_mul_f32 v[26:27], v[64:65], v[18:19] op_sel_hi:[1,0]
	v_pk_mul_f32 v[24:25], v[60:61], v[18:19] op_sel_hi:[1,0]
	v_pk_mul_f32 v[22:23], v[56:57], v[18:19] op_sel_hi:[1,0]
	v_pk_mul_f32 v[20:21], v[52:53], v[18:19] op_sel_hi:[1,0]
	v_pk_mul_f32 v[18:19], v[82:83], v[18:19] op_sel_hi:[1,0]
	ds_read_b64_tr_b16 v[72:73], v126
	ds_read_b64_tr_b16 v[74:75], v127
	ds_read_b64_tr_b16 v[76:77], v125
	ds_read_b64_tr_b16 v[78:79], v124
	v_cvt_pk_bf16_f32 v52, v158, v66
	v_cvt_pk_bf16_f32 v53, v160, v130
	v_cvt_pk_bf16_f32 v54, v131, v134
	v_cvt_pk_bf16_f32 v55, v135, v138
	v_cvt_pk_bf16_f32 v56, v139, v142
	v_cvt_pk_bf16_f32 v57, v143, v146
	s_waitcnt lgkmcnt(2)
	v_mfma_f32_32x32x16_bf16 v[2:17], v[72:75], v[52:55], v[2:17]
	v_cvt_pk_bf16_f32 v58, v147, v150
	v_cvt_pk_bf16_f32 v59, v151, v154
	v_cvt_pk_bf16_f32 v60, v159, v128
	v_cvt_pk_bf16_f32 v61, v161, v132
	v_cvt_pk_bf16_f32 v62, v133, v136
	v_cvt_pk_bf16_f32 v63, v137, v140
	v_cvt_pk_bf16_f32 v68, v141, v144
	s_waitcnt lgkmcnt(0)
	v_mfma_f32_32x32x16_bf16 v[18:33], v[76:79], v[52:55], v[18:33]
	ds_read_b64_tr_b16 v[52:53], v122
	ds_read_b64_tr_b16 v[54:55], v123
	ds_read_b64_tr_b16 v[72:73], v119
	ds_read_b64_tr_b16 v[74:75], v120
	v_cvt_pk_bf16_f32 v69, v145, v148
	v_cvt_pk_bf16_f32 v70, v149, v152
	v_cvt_pk_bf16_f32 v71, v153, v156
	s_waitcnt lgkmcnt(2)
	v_mfma_f32_32x32x16_bf16 v[2:17], v[52:55], v[56:59], v[2:17]
	s_waitcnt lgkmcnt(0)
	v_mfma_f32_32x32x16_bf16 v[18:33], v[72:75], v[56:59], v[18:33]
	ds_read_b64_tr_b16 v[52:53], v117
	ds_read_b64_tr_b16 v[54:55], v118
	ds_read_b64_tr_b16 v[56:57], v115
	ds_read_b64_tr_b16 v[58:59], v116
	s_waitcnt lgkmcnt(2)
	v_mfma_f32_32x32x16_bf16 v[2:17], v[52:55], v[60:63], v[2:17]
	s_waitcnt lgkmcnt(0)
	v_mfma_f32_32x32x16_bf16 v[18:33], v[56:59], v[60:63], v[18:33]
	ds_read_b64_tr_b16 v[52:53], v113
	ds_read_b64_tr_b16 v[54:55], v114
	ds_read_b64_tr_b16 v[56:57], v111
	ds_read_b64_tr_b16 v[58:59], v112
	s_waitcnt lgkmcnt(2)
	v_mfma_f32_32x32x16_bf16 v[2:17], v[52:55], v[68:71], v[2:17]
	s_waitcnt lgkmcnt(0)
	v_mfma_f32_32x32x16_bf16 v[18:33], v[56:59], v[68:71], v[18:33]

; #define LAS __attribute__((address_space(3)))
; #define MFMA32(a, b, c) __builtin_amdgcn_mfma_f32_32x32x16_bf16((a), (b), (c), 0, 0, 0)
; #define WG_BAR() do { asm volatile("s_waitcnt lgkmcnt(0)" ::: "memory"); __builtin_amdgcn_s_barrier(); asm volatile("" ::: "memory"); } while (0)
; #define ATT_DMA(t) do { const int t_ = (t) < NS ? (t) : NS - 1; const size_t ro_ = (size_t)TILE_ROW(t_) * ZC; LAS unsigned char* d_ = dk0 + ((t) % ATT_NB) * KV_BUF; \
;         __builtin_amdgcn_global_load_lds((const unsigned*)(gk + ro_), (LAS unsigned*)d_, 16, 0, 0); __builtin_amdgcn_global_load_lds((const unsigned*)(gv + ro_), (LAS unsigned*)(d_ + KV_TILE), 16, 0, 0); } while (0)
; template <class ScoreFn>
; __device__ __forceinline__ void attn_step(AttnState& st, const bf16x8 (&qf)[4], LAS unsigned char* kb, LAS unsigned char* vb, int lane, const ScoreFn& sf) {
;     const int r = lane & 31, h = lane >> 5;
;     f32x16 s0, s1;
; #pragma unroll
;     for (int i = 0; i < 16; ++i) { s0[i] = 0.f; s1[i] = 0.f; }
;     LAS unsigned char* kp = kb + r * KVP; const int kx = (h ^ (r & 7)) << 4;
; #pragma unroll
;     for (int ds = 0; ds < 4; ++ds) {
;         const bf16x8 k0 = *(const LAS bf16x8*)(kp + (kx ^ (ds << 5))), k1 = *(const LAS bf16x8*)(kp + 32 * KVP + (kx ^ (ds << 5)));
;         s0 = MFMA32(k0, qf[ds], s0); s1 = MFMA32(k1, qf[ds], s1);
;     }
;     float mt = NEG_BIG;
;     __builtin_amdgcn_sched_barrier(0);
; #pragma unroll
;     for (int i = 0; i < 16; ++i) { s0[i] = sf(s0[i], (i & 3) + 8 * (i >> 2), h, r); mt = fmaxf(mt, s0[i]); if ((i & 7) == 7) __builtin_amdgcn_sched_barrier(0); }
; #pragma unroll
;     for (int i = 0; i < 16; ++i) { s1[i] = sf(s1[i], 32 + (i & 3) + 8 * (i >> 2), h, r); mt = fmaxf(mt, s1[i]); if ((i & 7) == 7) __builtin_amdgcn_sched_barrier(0); }
;     mt = fmaxf(mt, __shfl_xor(mt, 32));
; template <bool ISB>
; __device__ __forceinline__ void attn_wg_item(Frame& F, int l, int idx) {
;     ...
;     for (int s = 0; s < NS; ++s) {
;         ATT_DMA(s + ATT_D);
;         asm volatile("s_waitcnt vmcnt(8)" ::: "memory");
;         WG_BAR();
;         LAS unsigned char* cur = ring + (s % ATT_NB) * KV_BUF;
;         if (s >= nloc) { ScorePlain sf; attn_step(st, qf, cur, cur + KV_TILE, lane, sf); }
.LBB0_618:
	s_mul_hi_u32 s1, s80, 0xaaaaaaab
	s_lshr_b32 s1, s1, 2
	s_mul_i32 s1, s1, 0x18000
	v_readlane_b32 s2, v253, 14
	s_sub_i32 s74, s2, s1
	v_readlane_b32 s2, v253, 16
	s_sub_i32 s1, s2, s1
	s_mul_hi_u32 s2, s82, 0xaaaaaaab
	s_lshr_b32 s2, s2, 2
	s_add_i32 s75, s82, 4
	s_mul_i32 s2, s2, 0x18000
	s_cmp_lt_i32 s82, s78
	v_subrev_u32_e32 v139, s2, v96
	v_subrev_u32_e32 v138, s2, v97
	v_subrev_u32_e32 v137, s2, v98
	v_subrev_u32_e32 v136, s2, v99
	v_subrev_u32_e32 v134, s2, v100
	v_subrev_u32_e32 v133, s2, v102
	v_subrev_u32_e32 v129, s2, v103
	v_subrev_u32_e32 v128, s2, v104
	v_subrev_u32_e32 v125, s2, v105
	v_subrev_u32_e32 v124, s2, v106
	v_subrev_u32_e32 v121, s2, v107
	v_subrev_u32_e32 v120, s2, v108
	v_subrev_u32_e32 v118, s2, v110
	v_subrev_u32_e32 v119, s2, v111
	v_subrev_u32_e32 v122, s2, v112
	v_subrev_u32_e32 v123, s2, v113
	v_subrev_u32_e32 v126, s2, v114
	v_subrev_u32_e32 v127, s2, v115
	v_subrev_u32_e32 v132, s2, v116
	v_subrev_u32_e32 v135, s2, v117
	s_cselect_b64 s[2:3], -1, 0
	s_and_b64 vcc, s[2:3], exec
	s_cselect_b32 s2, s75, s79
	s_cmp_lt_i32 s2, s78
	s_cselect_b32 s3, 0, s78
	s_cselect_b32 s75, s77, 0x2000
	s_sub_i32 s2, s2, s3
	s_lshl_b32 s2, s2, 6
	s_add_i32 s2, s2, s75
	s_add_i32 s3, s81, s74
	s_add_i32 m0, s3, 0
	v_mad_i64_i32 v[34:35], s[2:3], s2, v249, v[92:93]
	v_lshl_add_u64 v[36:37], v[34:35], 0, s[86:87]
	s_add_i32 s1, s81, s1
	global_load_lds_dwordx4 v[36:37], off
	v_lshl_add_u64 v[34:35], v[34:35], 0, s[96:97]
	s_add_i32 m0, s1, 0
	s_mov_b64 s[74:75], -1
	global_load_lds_dwordx4 v[34:35], off
	s_waitcnt vmcnt(8)
	s_waitcnt lgkmcnt(0)
	s_barrier
	s_cbranch_vccnz .LBB0_620
	s_add_i32 s1, s81, 0
	v_add_u32_e32 v38, s1, v139
	ds_read_b128 v[34:37], v38
	ds_read_b128 v[50:53], v38 offset:4096
	v_add_u32_e32 v58, s1, v138
	ds_read_b128 v[54:57], v58
	ds_read_b128 v[84:87], v58 offset:4096
	v_add_u32_e32 v59, s1, v137
	v_add_u32_e32 v58, s1, v136
	s_waitcnt lgkmcnt(0)
	v_mfma_f32_32x32x16_bf16 v[34:49], v[34:37], v[68:71], 0
	ds_read_b128 v[88:91], v59 offset:4096
	v_mfma_f32_32x32x16_bf16 v[34:49], v[54:57], v[72:75], v[34:49]
	ds_read_b128 v[54:57], v59
	s_waitcnt lgkmcnt(0)
	v_mfma_f32_32x32x16_bf16 v[34:49], v[54:57], v[76:79], v[34:49]
	ds_read_b128 v[54:57], v58
	ds_read_b128 v[140:143], v58 offset:4096
	s_waitcnt lgkmcnt(0)
	v_mfma_f32_32x32x16_bf16 v[34:49], v[54:57], v[80:83], v[34:49]
	v_mfma_f32_32x32x16_bf16 v[50:65], v[50:53], v[68:71], 0
	v_mfma_f32_32x32x16_bf16 v[50:65], v[84:87], v[72:75], v[50:65]
	v_mfma_f32_32x32x16_bf16 v[50:65], v[88:91], v[76:79], v[50:65]
	v_mfma_f32_32x32x16_bf16 v[50:65], v[140:143], v[80:83], v[50:65]
	s_nop 7
	v_mul_f32_e32 v66, 0x3e38aa3b, v34
	v_mul_f32_e32 v84, 0x3e38aa3b, v35
	s_mov_b32 s1, 0xf149f2ca
	v_max3_f32 v66, v66, s1, v84
	v_mul_f32_e32 v84, 0x3e38aa3b, v36
	v_mul_f32_e32 v85, 0x3e38aa3b, v37
	v_max3_f32 v66, v66, v84, v85
	v_mul_f32_e32 v84, 0x3e38aa3b, v38
	v_mul_f32_e32 v85, 0x3e38aa3b, v39
	v_max3_f32 v66, v66, v84, v85
	v_mul_f32_e32 v84, 0x3e38aa3b, v40
	v_mul_f32_e32 v85, 0x3e38aa3b, v41
	v_max3_f32 v66, v66, v84, v85
	v_mul_f32_e32 v84, 0x3e38aa3b, v42
	v_mul_f32_e32 v85, 0x3e38aa3b, v43
	v_max3_f32 v66, v66, v84, v85
	v_mul_f32_e32 v84, 0x3e38aa3b, v44
	v_mul_f32_e32 v85, 0x3e38aa3b, v45
	v_max3_f32 v66, v66, v84, v85
	v_mul_f32_e32 v84, 0x3e38aa3b, v46
	v_mul_f32_e32 v85, 0x3e38aa3b, v47
	v_max3_f32 v66, v66, v84, v85
	v_mul_f32_e32 v84, 0x3e38aa3b, v48
	v_mul_f32_e32 v85, 0x3e38aa3b, v49
	v_max3_f32 v66, v66, v84, v85
	v_mul_f32_e32 v84, 0x3e38aa3b, v50
	v_mul_f32_e32 v85, 0x3e38aa3b, v51
	v_max3_f32 v66, v66, v84, v85
	v_mul_f32_e32 v84, 0x3e38aa3b, v52
	v_mul_f32_e32 v85, 0x3e38aa3b, v53
	v_max3_f32 v66, v66, v84, v85
	v_mul_f32_e32 v84, 0x3e38aa3b, v54
	v_mul_f32_e32 v85, 0x3e38aa3b, v55
	v_max3_f32 v66, v66, v84, v85
	v_mul_f32_e32 v84, 0x3e38aa3b, v56
	v_mul_f32_e32 v85, 0x3e38aa3b, v57
	v_max3_f32 v66, v66, v84, v85
	v_mul_f32_e32 v84, 0x3e38aa3b, v58
	v_mul_f32_e32 v85, 0x3e38aa3b, v59
	v_max3_f32 v66, v66, v84, v85
	v_mul_f32_e32 v84, 0x3e38aa3b, v60
	v_mul_f32_e32 v85, 0x3e38aa3b, v61
	v_max3_f32 v66, v66, v84, v85
	v_mul_f32_e32 v84, 0x3e38aa3b, v62
	v_mul_f32_e32 v85, 0x3e38aa3b, v63
	v_max3_f32 v66, v66, v84, v85
	v_mul_f32_e32 v84, 0x3e38aa3b, v64
	v_mul_f32_e32 v85, 0x3e38aa3b, v65
	v_cmp_lt_i32_e32 vcc, v242, v241
	v_max3_f32 v66, v66, v84, v85
	s_nop 0
	v_cndmask_b32_e32 v84, v240, v242, vcc
	v_lshlrev_b32_e32 v84, 2, v84
	ds_bpermute_b32 v84, v84, v66
	s_waitcnt lgkmcnt(0)
; #define LAS __attribute__((address_space(3)))
; #define MFMA32(a, b, c) __builtin_amdgcn_mfma_f32_32x32x16_bf16((a), (b), (c), 0, 0, 0)
; __device__ __forceinline__ s16x4 tr_read(LAS unsigned char* p) { return __builtin_bit_cast(s16x4, __builtin_amdgcn_ds_read_tr16_b64_v4i16((LAS v4i16_t*)p)); }
; template <class ScoreFn>
; __device__ __forceinline__ void attn_step(AttnState& st, const bf16x8 (&qf)[4], LAS unsigned char* kb, LAS unsigned char* vb, int lane, const ScoreFn& sf) {
;     ...
;     const float mn = fmaxf(st.m, mt), alpha = __builtin_amdgcn_exp2f(st.m - mn);
;     float ps = 0.f;
; #pragma unroll
;     for (int i = 0; i < 16; ++i) { s0[i] = __builtin_amdgcn_exp2f(s0[i] - mn); s1[i] = __builtin_amdgcn_exp2f(s1[i] - mn); ps += s0[i] + s1[i]; }
;     st.l = st.l * alpha + ps; st.m = mn;
; #pragma unroll
;     for (int i = 0; i < 16; ++i) { st.o0[i] *= alpha; st.o1[i] *= alpha; }
;     __builtin_amdgcn_sched_barrier(0);
;     v4u pw[4];
;     pw[0].x = cvtpk(s0[0], s0[1]); pw[0].y = cvtpk(s0[2], s0[3]); pw[0].z = cvtpk(s0[4], s0[5]); pw[0].w = cvtpk(s0[6], s0[7]);
;     pw[1].x = cvtpk(s0[8], s0[9]); pw[1].y = cvtpk(s0[10], s0[11]); pw[1].z = cvtpk(s0[12], s0[13]); pw[1].w = cvtpk(s0[14], s0[15]);
;     pw[2].x = cvtpk(s1[0], s1[1]); pw[2].y = cvtpk(s1[2], s1[3]); pw[2].z = cvtpk(s1[4], s1[5]); pw[2].w = cvtpk(s1[6], s1[7]);
;     pw[3].x = cvtpk(s1[8], s1[9]); pw[3].y = cvtpk(s1[10], s1[11]); pw[3].z = cvtpk(s1[12], s1[13]); pw[3].w = cvtpk(s1[14], s1[15]);
;     const int i16 = lane & 15, q = i16 >> 2, p = i16 & 3, dhalf = (lane >> 4) & 1;
;     LAS unsigned char* vrow = vb + (4 * h + q) * KVP + (p & 1) * 8;
;     LAS unsigned char* vp0 = vrow + (((2 * dhalf + (p >> 1)) ^ (4 * h + q)) << 4); LAS unsigned char* vp1 = vrow + (((4 + 2 * dhalf + (p >> 1)) ^ (4 * h + q)) << 4);
; #pragma unroll
;     for (int ks = 0; ks < 4; ++ks) {
;         const s16x4 l0 = tr_read(vp0 + (16 * ks) * KVP), h0 = tr_read(vp0 + (16 * ks + 8) * KVP);
;         const s16x4 l1 = tr_read(vp1 + (16 * ks) * KVP), h1 = tr_read(vp1 + (16 * ks + 8) * KVP);
;         const bf16x8 v0 = (bf16x8){l0[0], l0[1], l0[2], l0[3], h0[0], h0[1], h0[2], h0[3]};
;         const bf16x8 v1 = (bf16x8){l1[0], l1[1], l1[2], l1[3], h1[0], h1[1], h1[2], h1[3]};
;         const bf16x8 pf = __builtin_bit_cast(bf16x8, pw[ks]);
;         st.o0 = MFMA32(v0, pf, st.o0); st.o1 = MFMA32(v1, pf, st.o1);
;     }
	v_max3_f32 v140, v131, v66, v84
	v_fma_f32 v34, v34, s0, -v140
	v_exp_f32_e32 v142, v34
	v_fma_f32 v34, v50, s0, -v140
	v_exp_f32_e32 v165, v34
	v_fma_f32 v34, v35, s0, -v140
	v_exp_f32_e32 v66, v34
	v_fma_f32 v34, v51, s0, -v140
	v_exp_f32_e32 v84, v34
	v_add_f32_e32 v85, v165, v142
	v_pk_add_f32 v[34:35], v[84:85], v[66:67]
	s_nop 0
	v_pk_add_f32 v[86:87], v[34:35], v[34:35] op_sel_hi:[0,1]
	v_fma_f32 v34, v36, s0, -v140
	v_exp_f32_e32 v85, v34
	v_fma_f32 v34, v52, s0, -v140
	v_exp_f32_e32 v170, v34
	v_fma_f32 v34, v37, s0, -v140
	v_exp_f32_e32 v86, v34
	v_fma_f32 v34, v53, s0, -v140
	v_exp_f32_e32 v90, v34
	v_add_f32_e32 v91, v170, v85
	v_pk_add_f32 v[34:35], v[90:91], v[86:87]
	s_nop 0
	v_pk_add_f32 v[88:89], v[34:35], v[34:35] op_sel_hi:[0,1]
	v_fma_f32 v34, v38, s0, -v140
	v_exp_f32_e32 v87, v34
	v_fma_f32 v34, v54, s0, -v140
	v_exp_f32_e32 v91, v34
	v_fma_f32 v34, v39, s0, -v140
	v_exp_f32_e32 v88, v34
	v_fma_f32 v34, v55, s0, -v140
	v_exp_f32_e32 v150, v34
	v_add_f32_e32 v151, v91, v87
	v_pk_add_f32 v[34:35], v[150:151], v[88:89]
	s_nop 0
	v_pk_add_f32 v[146:147], v[34:35], v[34:35] op_sel_hi:[0,1]
	v_fma_f32 v34, v40, s0, -v140
	v_exp_f32_e32 v89, v34
	v_fma_f32 v34, v56, s0, -v140
	v_exp_f32_e32 v151, v34
	v_fma_f32 v34, v41, s0, -v140
	v_exp_f32_e32 v146, v34
	v_fma_f32 v34, v57, s0, -v140
	v_exp_f32_e32 v152, v34
	v_add_f32_e32 v153, v151, v89
	v_pk_add_f32 v[34:35], v[152:153], v[146:147]
	s_nop 0
	v_pk_add_f32 v[148:149], v[34:35], v[34:35] op_sel_hi:[0,1]
	v_fma_f32 v34, v42, s0, -v140
	v_exp_f32_e32 v147, v34
	v_fma_f32 v34, v58, s0, -v140
	v_exp_f32_e32 v153, v34
	v_fma_f32 v34, v43, s0, -v140
	v_exp_f32_e32 v148, v34
	v_fma_f32 v34, v59, s0, -v140
	v_exp_f32_e32 v154, v34
	v_add_f32_e32 v155, v153, v147
	v_pk_add_f32 v[34:35], v[154:155], v[148:149]
	s_nop 0
	v_pk_add_f32 v[156:157], v[34:35], v[34:35] op_sel_hi:[0,1]
	v_fma_f32 v34, v44, s0, -v140
	v_exp_f32_e32 v149, v34
	v_fma_f32 v34, v60, s0, -v140
	v_exp_f32_e32 v155, v34
	v_fma_f32 v34, v45, s0, -v140
	v_exp_f32_e32 v156, v34
	v_fma_f32 v34, v61, s0, -v140
	v_exp_f32_e32 v158, v34
	v_add_f32_e32 v159, v155, v149
	v_pk_add_f32 v[34:35], v[158:159], v[156:157]
	s_nop 0
	v_pk_add_f32 v[160:161], v[34:35], v[34:35] op_sel_hi:[0,1]
	v_fma_f32 v34, v46, s0, -v140
	v_exp_f32_e32 v157, v34
	v_fma_f32 v34, v62, s0, -v140
	v_exp_f32_e32 v159, v34
	v_fma_f32 v34, v47, s0, -v140
	v_exp_f32_e32 v160, v34
	v_fma_f32 v34, v63, s0, -v140
	v_exp_f32_e32 v162, v34
	v_add_f32_e32 v163, v159, v157
	v_pk_add_f32 v[34:35], v[162:163], v[160:161]
	s_nop 0
	v_pk_add_f32 v[166:167], v[34:35], v[34:35] op_sel_hi:[0,1]
	v_fma_f32 v34, v48, s0, -v140
	v_exp_f32_e32 v161, v34
	v_fma_f32 v34, v64, s0, -v140
	v_exp_f32_e32 v163, v34
	v_fma_f32 v34, v49, s0, -v140
	v_exp_f32_e32 v166, v34
	v_fma_f32 v34, v65, s0, -v140
	v_exp_f32_e32 v168, v34
	v_sub_f32_e32 v34, v131, v140
	v_exp_f32_e32 v50, v34
	v_add_f32_e32 v169, v163, v161
	v_pk_add_f32 v[34:35], v[168:169], v[166:167]
	v_pk_mul_f32 v[48:49], v[32:33], v[50:51] op_sel_hi:[1,0]
	v_add_f32_e32 v141, v34, v35
	v_fmac_f32_e32 v141, v130, v50
	v_pk_mul_f32 v[46:47], v[30:31], v[50:51] op_sel_hi:[1,0]
	v_pk_mul_f32 v[44:45], v[28:29], v[50:51] op_sel_hi:[1,0]
	v_pk_mul_f32 v[42:43], v[26:27], v[50:51] op_sel_hi:[1,0]
	v_pk_mul_f32 v[40:41], v[24:25], v[50:51] op_sel_hi:[1,0]
	v_pk_mul_f32 v[38:39], v[22:23], v[50:51] op_sel_hi:[1,0]
	v_pk_mul_f32 v[36:37], v[20:21], v[50:51] op_sel_hi:[1,0]
	v_pk_mul_f32 v[34:35], v[18:19], v[50:51] op_sel_hi:[1,0]
	v_pk_mul_f32 v[64:65], v[16:17], v[50:51] op_sel_hi:[1,0]
	v_pk_mul_f32 v[62:63], v[14:15], v[50:51] op_sel_hi:[1,0]
	v_pk_mul_f32 v[60:61], v[12:13], v[50:51] op_sel_hi:[1,0]
	v_pk_mul_f32 v[58:59], v[10:11], v[50:51] op_sel_hi:[1,0]
	v_pk_mul_f32 v[56:57], v[8:9], v[50:51] op_sel_hi:[1,0]
	v_pk_mul_f32 v[54:55], v[6:7], v[50:51] op_sel_hi:[1,0]
	v_pk_mul_f32 v[52:53], v[4:5], v[50:51] op_sel_hi:[1,0]
	v_pk_mul_f32 v[50:51], v[2:3], v[50:51] op_sel_hi:[1,0]
	v_cvt_pk_bf16_f32 v142, v142, v66
	v_add3_u32 v66, s81, v134, v101
	v_cvt_pk_bf16_f32 v144, v87, v88
	v_cvt_pk_bf16_f32 v145, v89, v146
	v_cvt_pk_bf16_f32 v88, v165, v84
	v_cvt_pk_bf16_f32 v89, v170, v90
	v_cvt_pk_bf16_f32 v90, v91, v150
	v_cvt_pk_bf16_f32 v91, v151, v152
	v_cvt_pk_bf16_f32 v84, v153, v154
	v_add3_u32 v154, s81, v135, v101
	ds_read_b64_tr_b16 v[150:151], v66
	v_add3_u32 v66, s81, v133, v101
	v_cvt_pk_bf16_f32 v143, v85, v86
	v_cvt_pk_bf16_f32 v85, v155, v158
	ds_read_b64_tr_b16 v[152:153], v66
	ds_read_b64_tr_b16 v[154:155], v154
	v_add3_u32 v66, s81, v132, v101
	v_cvt_pk_bf16_f32 v146, v147, v148
	v_cvt_pk_bf16_f32 v147, v149, v156
	v_cvt_pk_bf16_f32 v148, v157, v160
	ds_read_b64_tr_b16 v[156:157], v66
	v_add3_u32 v66, s81, v129, v101
	s_waitcnt lgkmcnt(2)
	v_mfma_f32_32x32x16_bf16 v[34:49], v[150:153], v[142:145], v[34:49]
	v_cvt_pk_bf16_f32 v149, v161, v166
	v_cvt_pk_bf16_f32 v86, v159, v162
	v_cvt_pk_bf16_f32 v87, v163, v168
	s_mov_b64 s[74:75], 0
	s_waitcnt lgkmcnt(0)
	v_mfma_f32_32x32x16_bf16 v[50:65], v[154:157], v[142:145], v[50:65]
	ds_read_b64_tr_b16 v[142:143], v66
	v_add3_u32 v66, s81, v128, v101
	ds_read_b64_tr_b16 v[144:145], v66
	v_add3_u32 v66, s81, v127, v101
	ds_read_b64_tr_b16 v[150:151], v66
	v_add3_u32 v66, s81, v126, v101
	ds_read_b64_tr_b16 v[152:153], v66
	v_add3_u32 v66, s81, v125, v101
	s_waitcnt lgkmcnt(2)
	v_mfma_f32_32x32x16_bf16 v[34:49], v[142:145], v[146:149], v[34:49]
	ds_read_b64_tr_b16 v[142:143], v66
	v_add3_u32 v66, s81, v124, v101
	ds_read_b64_tr_b16 v[144:145], v66
	v_add3_u32 v66, s81, v123, v101
	s_waitcnt lgkmcnt(2)
	v_mfma_f32_32x32x16_bf16 v[50:65], v[150:153], v[146:149], v[50:65]
	ds_read_b64_tr_b16 v[146:147], v66
	v_add3_u32 v66, s81, v122, v101
	ds_read_b64_tr_b16 v[148:149], v66
	v_add3_u32 v66, s81, v121, v101
	s_waitcnt lgkmcnt(2)
	v_mfma_f32_32x32x16_bf16 v[34:49], v[142:145], v[88:91], v[34:49]
	s_waitcnt lgkmcnt(0)
	v_mfma_f32_32x32x16_bf16 v[50:65], v[146:149], v[88:91], v[50:65]
	ds_read_b64_tr_b16 v[88:89], v66
	v_add3_u32 v66, s81, v120, v101
	ds_read_b64_tr_b16 v[90:91], v66
	v_add3_u32 v66, s81, v119, v101
	ds_read_b64_tr_b16 v[142:143], v66
	v_add3_u32 v66, s81, v118, v101
	ds_read_b64_tr_b16 v[144:145], v66
	s_waitcnt lgkmcnt(2)
	v_mfma_f32_32x32x16_bf16 v[34:49], v[88:91], v[84:87], v[34:49]
	s_waitcnt lgkmcnt(0)
	v_mfma_f32_32x32x16_bf16 v[50:65], v[142:145], v[84:87], v[50:65]
; #define LAS __attribute__((address_space(3)))
; #define MFMA32(a, b, c) __builtin_amdgcn_mfma_f32_32x32x16_bf16((a), (b), (c), 0, 0, 0)
;     __device__ __forceinline__ float operator()(float s, int kc, int h, int qr) const { const int d = dk + kc + 4 * h - qr; return (d >= -128 && d <= 128) ? s * (ATT_SCALE * LOG2E) : NEG_BIG; }
; template <class ScoreFn>
; __device__ __forceinline__ void attn_step(AttnState& st, const bf16x8 (&qf)[4], LAS unsigned char* kb, LAS unsigned char* vb, int lane, const ScoreFn& sf) {
;     const int r = lane & 31, h = lane >> 5;
;     f32x16 s0, s1;
; #pragma unroll
;     for (int i = 0; i < 16; ++i) { s0[i] = 0.f; s1[i] = 0.f; }
;     LAS unsigned char* kp = kb + r * KVP; const int kx = (h ^ (r & 7)) << 4;
; #pragma unroll
;     for (int ds = 0; ds < 4; ++ds) {
;         const bf16x8 k0 = *(const LAS bf16x8*)(kp + (kx ^ (ds << 5))), k1 = *(const LAS bf16x8*)(kp + 32 * KVP + (kx ^ (ds << 5)));
;         s0 = MFMA32(k0, qf[ds], s0); s1 = MFMA32(k1, qf[ds], s1);
;     }
;     float mt = NEG_BIG;
;     __builtin_amdgcn_sched_barrier(0);
; #pragma unroll
;     for (int i = 0; i < 16; ++i) { s0[i] = sf(s0[i], (i & 3) + 8 * (i >> 2), h, r); mt = fmaxf(mt, s0[i]); if ((i & 7) == 7) __builtin_amdgcn_sched_barrier(0); }
; #pragma unroll
;     for (int i = 0; i < 16; ++i) { s1[i] = sf(s1[i], 32 + (i & 3) + 8 * (i >> 2), h, r); mt = fmaxf(mt, s1[i]); if ((i & 7) == 7) __builtin_amdgcn_sched_barrier(0); }
;     mt = fmaxf(mt, __shfl_xor(mt, 32));
;     __device__ __forceinline__ float operator()(float s, int kc, int, int) const {
;         const float b = *(const LAS float*)(tbs + 4 * kc);
;         return (kc >= lo4 && kc < lo4 + 16) ? fmaf(s, ATT_SCALE * LOG2E, b) : NEG_BIG;
;     }
.LBB0_620:
	s_andn2_b64 vcc, exec, s[74:75]
	s_cbranch_vccnz .LBB0_624
	s_add_i32 s1, s76, s82
	v_cmp_ge_u32_e32 vcc, s1, v94
	v_cmp_lt_u32_e64 s[74:75], s1, v95
	s_and_b64 s[2:3], vcc, s[74:75]
	s_andn2_b64 vcc, exec, s[2:3]
	s_cbranch_vccnz .LBB0_623
	s_add_i32 s1, s81, 0
	s_nop 0
	v_add_u32_e32 v38, s1, v139
	ds_read_b128 v[34:37], v38
	ds_read_b128 v[50:53], v38 offset:4096
	v_add_u32_e32 v58, s1, v138
	ds_read_b128 v[54:57], v58
	ds_read_b128 v[84:87], v58 offset:4096
	v_add_u32_e32 v59, s1, v137
	v_add_u32_e32 v58, s1, v136
	v_add_u32_e32 v66, 0, v109
	s_waitcnt lgkmcnt(0)
	v_mfma_f32_32x32x16_bf16 v[34:49], v[34:37], v[68:71], 0
	ds_read_b128 v[88:91], v59 offset:4096
	ds_read_b128 v[136:139], v58 offset:4096
	v_mfma_f32_32x32x16_bf16 v[34:49], v[54:57], v[72:75], v[34:49]
	ds_read_b128 v[54:57], v59
	v_add_u32_e32 v59, 0x184a0, v66
	s_waitcnt lgkmcnt(0)
	v_mfma_f32_32x32x16_bf16 v[34:49], v[54:57], v[76:79], v[34:49]
	ds_read_b128 v[54:57], v58
	s_waitcnt lgkmcnt(0)
	v_mfma_f32_32x32x16_bf16 v[34:49], v[54:57], v[80:83], v[34:49]
	v_add_u32_e32 v54, 0x184a8, v66
	v_add_u32_e32 v55, 0x184c0, v66
	v_add_u32_e32 v56, 0x184c8, v66
	ds_read2_b32 v[140:141], v59 offset1:1
	ds_read2_b32 v[142:143], v54 offset1:1
	ds_read2_b32 v[144:145], v55 offset1:1
	ds_read2_b32 v[146:147], v56 offset1:1
	v_add_u32_e32 v54, 0x184e0, v66
	v_add_u32_e32 v55, 0x184e8, v66
	v_add_u32_e32 v56, 0x18500, v66
	v_add_u32_e32 v57, 0x18508, v66
	ds_read2_b32 v[148:149], v54 offset1:1
	ds_read2_b32 v[150:151], v55 offset1:1
	ds_read2_b32 v[152:153], v56 offset1:1
	ds_read2_b32 v[154:155], v57 offset1:1
	v_mfma_f32_32x32x16_bf16 v[50:65], v[50:53], v[68:71], 0
	v_mfma_f32_32x32x16_bf16 v[50:65], v[84:87], v[72:75], v[50:65]
	v_add_u32_e32 v84, 0x18520, v66
	v_add_u32_e32 v86, 0x18528, v66
	v_mfma_f32_32x32x16_bf16 v[50:65], v[88:91], v[76:79], v[50:65]
	v_add_u32_e32 v88, 0x18540, v66
	v_add_u32_e32 v90, 0x18548, v66
	ds_read2_b32 v[84:85], v84 offset1:1
	ds_read2_b32 v[86:87], v86 offset1:1
	ds_read2_b32 v[88:89], v88 offset1:1
	ds_read2_b32 v[90:91], v90 offset1:1
	v_mfma_f32_32x32x16_bf16 v[50:65], v[136:139], v[80:83], v[50:65]
	v_add_u32_e32 v136, 0x18560, v66
	v_add_u32_e32 v138, 0x18568, v66
	v_add_u32_e32 v156, 0x18580, v66
	v_add_u32_e32 v66, 0x18588, v66
	ds_read2_b32 v[136:137], v136 offset1:1
	ds_read2_b32 v[138:139], v138 offset1:1
	ds_read2_b32 v[156:157], v156 offset1:1
	ds_read2_b32 v[158:159], v66 offset1:1
	s_waitcnt lgkmcnt(0)
	v_fmamk_f32 v34, v34, 0x3e38aa3b, v140
	v_fmac_f32_e32 v141, 0x3e38aa3b, v35
	v_cndmask_b32_e64 v34, v250, v34, s[6:7]
	v_cndmask_b32_e64 v35, v250, v141, s[8:9]
	s_mov_b32 s1, 0xf149f2ca
	v_fmamk_f32 v36, v36, 0x3e38aa3b, v142
	v_fmac_f32_e32 v143, 0x3e38aa3b, v37
	v_max3_f32 v66, v34, s1, v35
	v_cndmask_b32_e64 v140, v250, v36, s[10:11]
	v_cndmask_b32_e64 v141, v250, v143, s[12:13]
	v_fmamk_f32 v37, v38, 0x3e38aa3b, v144
	v_fmac_f32_e32 v145, 0x3e38aa3b, v39
	v_max3_f32 v36, v66, v140, v141
	v_cndmask_b32_e64 v142, v250, v37, s[14:15]
	v_cndmask_b32_e64 v143, v250, v145, s[16:17]
	v_fmamk_f32 v37, v40, 0x3e38aa3b, v146
	v_fmac_f32_e32 v147, 0x3e38aa3b, v41
	v_max3_f32 v36, v36, v142, v143
	v_cndmask_b32_e64 v144, v250, v37, s[18:19]
	v_cndmask_b32_e64 v145, v250, v147, s[20:21]
	v_fmamk_f32 v37, v42, 0x3e38aa3b, v148
	v_fmac_f32_e32 v149, 0x3e38aa3b, v43
	v_max3_f32 v36, v36, v144, v145
	v_cndmask_b32_e64 v146, v250, v37, s[22:23]
	v_cndmask_b32_e64 v43, v250, v149, s[24:25]
	v_fmamk_f32 v37, v44, 0x3e38aa3b, v150
	v_fmac_f32_e32 v151, 0x3e38aa3b, v45
	v_max3_f32 v36, v36, v146, v43
	v_cndmask_b32_e64 v147, v250, v37, s[26:27]
	v_cndmask_b32_e64 v148, v250, v151, s[28:29]
	v_fmamk_f32 v37, v46, 0x3e38aa3b, v152
	v_fmac_f32_e32 v153, 0x3e38aa3b, v47
	v_max3_f32 v36, v36, v147, v148
	v_cndmask_b32_e64 v46, v250, v37, s[30:31]
	v_cndmask_b32_e64 v47, v250, v153, s[34:35]
	v_fmamk_f32 v37, v48, 0x3e38aa3b, v154
	v_fmac_f32_e32 v155, 0x3e38aa3b, v49
	v_max3_f32 v36, v36, v46, v47
	v_cndmask_b32_e64 v149, v250, v37, s[36:37]
	v_cndmask_b32_e64 v150, v250, v155, s[38:39]
	v_fmamk_f32 v37, v50, 0x3e38aa3b, v84
	v_fmac_f32_e32 v85, 0x3e38aa3b, v51
	v_max3_f32 v36, v36, v149, v150
	v_cndmask_b32_e64 v37, v250, v37, s[40:41]
	v_cndmask_b32_e64 v38, v250, v85, s[42:43]
	v_fmamk_f32 v39, v52, 0x3e38aa3b, v86
	v_fmac_f32_e32 v87, 0x3e38aa3b, v53
	v_max3_f32 v36, v36, v37, v38
	v_cndmask_b32_e64 v39, v250, v39, s[44:45]
	v_cndmask_b32_e64 v40, v250, v87, s[46:47]
	v_fmamk_f32 v41, v54, 0x3e38aa3b, v88
	v_fmac_f32_e32 v89, 0x3e38aa3b, v55
	v_max3_f32 v36, v36, v39, v40
	v_cndmask_b32_e64 v44, v250, v41, s[48:49]
	v_cndmask_b32_e64 v45, v250, v89, s[50:51]
	v_fmamk_f32 v41, v56, 0x3e38aa3b, v90
	v_fmac_f32_e32 v91, 0x3e38aa3b, v57
	v_max3_f32 v36, v36, v44, v45
	v_cndmask_b32_e64 v50, v250, v41, s[52:53]
	v_cndmask_b32_e64 v51, v250, v91, s[54:55]
	v_fmamk_f32 v41, v58, 0x3e38aa3b, v136
	v_fmac_f32_e32 v137, 0x3e38aa3b, v59
	v_max3_f32 v36, v36, v50, v51
	v_cndmask_b32_e64 v56, v250, v41, s[56:57]
	v_cndmask_b32_e64 v57, v250, v137, s[58:59]
	v_fmamk_f32 v41, v60, 0x3e38aa3b, v138
	v_fmac_f32_e32 v139, 0x3e38aa3b, v61
	v_max3_f32 v36, v36, v56, v57
	v_cndmask_b32_e64 v60, v250, v41, s[60:61]
	v_cndmask_b32_e64 v61, v250, v139, s[62:63]
	v_fmamk_f32 v41, v62, 0x3e38aa3b, v156
	v_fmac_f32_e32 v157, 0x3e38aa3b, v63
	v_max3_f32 v36, v36, v60, v61
	v_cndmask_b32_e64 v84, v250, v41, s[64:65]
	v_cndmask_b32_e64 v85, v250, v157, s[66:67]
	v_fmamk_f32 v41, v64, 0x3e38aa3b, v158
	v_fmac_f32_e32 v159, 0x3e38aa3b, v65
	v_cmp_lt_i32_e32 vcc, v242, v241
	v_max3_f32 v36, v36, v84, v85
	v_cndmask_b32_e64 v86, v250, v41, s[68:69]
	v_cndmask_b32_e64 v87, v250, v159, s[70:71]
	v_cndmask_b32_e32 v41, v240, v242, vcc
	v_max3_f32 v36, v36, v86, v87
	v_lshlrev_b32_e32 v41, 2, v41
	ds_bpermute_b32 v41, v41, v36
	s_waitcnt lgkmcnt(0)
; #define LAS __attribute__((address_space(3)))
; #define MFMA32(a, b, c) __builtin_amdgcn_mfma_f32_32x32x16_bf16((a), (b), (c), 0, 0, 0)
; __device__ __forceinline__ s16x4 tr_read(LAS unsigned char* p) { return __builtin_bit_cast(s16x4, __builtin_amdgcn_ds_read_tr16_b64_v4i16((LAS v4i16_t*)p)); }
; template <class ScoreFn>
; __device__ __forceinline__ void attn_step(AttnState& st, const bf16x8 (&qf)[4], LAS unsigned char* kb, LAS unsigned char* vb, int lane, const ScoreFn& sf) {
;     ...
;     const float mn = fmaxf(st.m, mt), alpha = __builtin_amdgcn_exp2f(st.m - mn);
;     float ps = 0.f;
; #pragma unroll
;     for (int i = 0; i < 16; ++i) { s0[i] = __builtin_amdgcn_exp2f(s0[i] - mn); s1[i] = __builtin_amdgcn_exp2f(s1[i] - mn); ps += s0[i] + s1[i]; }
;     st.l = st.l * alpha + ps; st.m = mn;
; #pragma unroll
;     for (int i = 0; i < 16; ++i) { st.o0[i] *= alpha; st.o1[i] *= alpha; }
;     __builtin_amdgcn_sched_barrier(0);
;     v4u pw[4];
;     pw[0].x = cvtpk(s0[0], s0[1]); pw[0].y = cvtpk(s0[2], s0[3]); pw[0].z = cvtpk(s0[4], s0[5]); pw[0].w = cvtpk(s0[6], s0[7]);
;     pw[1].x = cvtpk(s0[8], s0[9]); pw[1].y = cvtpk(s0[10], s0[11]); pw[1].z = cvtpk(s0[12], s0[13]); pw[1].w = cvtpk(s0[14], s0[15]);
;     pw[2].x = cvtpk(s1[0], s1[1]); pw[2].y = cvtpk(s1[2], s1[3]); pw[2].z = cvtpk(s1[4], s1[5]); pw[2].w = cvtpk(s1[6], s1[7]);
;     pw[3].x = cvtpk(s1[8], s1[9]); pw[3].y = cvtpk(s1[10], s1[11]); pw[3].z = cvtpk(s1[12], s1[13]); pw[3].w = cvtpk(s1[14], s1[15]);
;     const int i16 = lane & 15, q = i16 >> 2, p = i16 & 3, dhalf = (lane >> 4) & 1;
;     LAS unsigned char* vrow = vb + (4 * h + q) * KVP + (p & 1) * 8;
;     LAS unsigned char* vp0 = vrow + (((2 * dhalf + (p >> 1)) ^ (4 * h + q)) << 4); LAS unsigned char* vp1 = vrow + (((4 + 2 * dhalf + (p >> 1)) ^ (4 * h + q)) << 4);
; #pragma unroll
;     for (int ks = 0; ks < 4; ++ks) {
;         const s16x4 l0 = tr_read(vp0 + (16 * ks) * KVP), h0 = tr_read(vp0 + (16 * ks + 8) * KVP);
;         const s16x4 l1 = tr_read(vp1 + (16 * ks) * KVP), h1 = tr_read(vp1 + (16 * ks + 8) * KVP);
;         const bf16x8 v0 = (bf16x8){l0[0], l0[1], l0[2], l0[3], h0[0], h0[1], h0[2], h0[3]};
;         const bf16x8 v1 = (bf16x8){l1[0], l1[1], l1[2], l1[3], h1[0], h1[1], h1[2], h1[3]};
;         const bf16x8 pf = __builtin_bit_cast(bf16x8, pw[ks]);
;         st.o0 = MFMA32(v0, pf, st.o0); st.o1 = MFMA32(v1, pf, st.o1);
;     }
	v_max3_f32 v42, v131, v36, v41
	v_sub_f32_e32 v34, v34, v42
	v_exp_f32_e32 v88, v34
	v_sub_f32_e32 v34, v37, v42
	v_exp_f32_e32 v89, v34
	v_sub_f32_e32 v34, v35, v42
	v_exp_f32_e32 v66, v34
	v_sub_f32_e32 v34, v38, v42
	v_exp_f32_e32 v34, v34
	v_add_f32_e32 v35, v89, v88
	v_sub_f32_e32 v38, v40, v42
	v_exp_f32_e32 v40, v38
	v_pk_add_f32 v[36:37], v[34:35], v[66:67]
	v_sub_f32_e32 v35, v140, v42
	v_pk_add_f32 v[36:37], v[36:37], v[36:37] op_sel_hi:[0,1]
	v_sub_f32_e32 v36, v39, v42
	v_exp_f32_e32 v35, v35
	v_exp_f32_e32 v90, v36
	v_sub_f32_e32 v36, v141, v42
	v_exp_f32_e32 v36, v36
	v_sub_f32_e32 v43, v43, v42
	v_add_f32_e32 v41, v90, v35
	v_pk_add_f32 v[38:39], v[40:41], v[36:37]
	s_nop 0
	v_pk_add_f32 v[38:39], v[38:39], v[38:39] op_sel_hi:[0,1]
	v_sub_f32_e32 v37, v142, v42
	v_sub_f32_e32 v38, v44, v42
	v_exp_f32_e32 v37, v37
	v_exp_f32_e32 v41, v38
	v_sub_f32_e32 v38, v143, v42
	v_sub_f32_e32 v44, v45, v42
	v_exp_f32_e32 v38, v38
	v_exp_f32_e32 v52, v44
	v_add_f32_e32 v53, v41, v37
	v_pk_add_f32 v[44:45], v[52:53], v[38:39]
	s_nop 0
	v_pk_add_f32 v[48:49], v[44:45], v[44:45] op_sel_hi:[0,1]
	v_sub_f32_e32 v44, v50, v42
	v_sub_f32_e32 v39, v144, v42
	v_exp_f32_e32 v53, v44
	v_sub_f32_e32 v44, v145, v42
	v_exp_f32_e32 v39, v39
	v_exp_f32_e32 v48, v44
	v_sub_f32_e32 v44, v51, v42
	v_exp_f32_e32 v54, v44
	v_add_f32_e32 v55, v53, v39
	v_pk_add_f32 v[44:45], v[54:55], v[48:49]
	s_nop 0
	v_pk_add_f32 v[50:51], v[44:45], v[44:45] op_sel_hi:[0,1]
	v_sub_f32_e32 v44, v146, v42
	v_exp_f32_e32 v49, v44
	v_sub_f32_e32 v44, v56, v42
	v_exp_f32_e32 v55, v44
	v_exp_f32_e32 v50, v43
	v_sub_f32_e32 v43, v57, v42
	v_exp_f32_e32 v56, v43
	v_add_f32_e32 v57, v55, v49
	v_sub_f32_e32 v43, v147, v42
	v_exp_f32_e32 v43, v43
	v_pk_add_f32 v[44:45], v[56:57], v[50:51]
	s_nop 0
	v_pk_add_f32 v[58:59], v[44:45], v[44:45] op_sel_hi:[0,1]
	v_sub_f32_e32 v44, v60, v42
	v_exp_f32_e32 v57, v44
	v_sub_f32_e32 v44, v148, v42
	v_exp_f32_e32 v58, v44
	v_sub_f32_e32 v44, v61, v42
	v_exp_f32_e32 v60, v44
	v_add_f32_e32 v61, v57, v43
	v_pk_add_f32 v[44:45], v[60:61], v[58:59]
	s_nop 0
	v_pk_add_f32 v[62:63], v[44:45], v[44:45] op_sel_hi:[0,1]
	v_sub_f32_e32 v44, v46, v42
	v_exp_f32_e32 v51, v44
	v_sub_f32_e32 v44, v84, v42
	v_exp_f32_e32 v59, v44
	v_sub_f32_e32 v44, v47, v42
	v_exp_f32_e32 v62, v44
	v_sub_f32_e32 v44, v85, v42
	v_exp_f32_e32 v64, v44
	v_add_f32_e32 v65, v59, v51
	v_pk_add_f32 v[44:45], v[64:65], v[62:63]
	s_nop 0
	v_pk_add_f32 v[84:85], v[44:45], v[44:45] op_sel_hi:[0,1]
	v_sub_f32_e32 v44, v149, v42
	v_exp_f32_e32 v61, v44
	v_sub_f32_e32 v44, v86, v42
	v_exp_f32_e32 v63, v44
	v_sub_f32_e32 v44, v150, v42
	v_exp_f32_e32 v84, v44
	v_sub_f32_e32 v44, v87, v42
	v_exp_f32_e32 v86, v44
	v_sub_f32_e32 v44, v131, v42
	v_exp_f32_e32 v44, v44
	v_add_f32_e32 v87, v63, v61
	v_pk_add_f32 v[46:47], v[86:87], v[84:85]
	v_pk_mul_f32 v[32:33], v[32:33], v[44:45] op_sel_hi:[1,0]
	v_add_f32_e32 v65, v46, v47
	v_pk_mul_f32 v[30:31], v[30:31], v[44:45] op_sel_hi:[1,0]
	v_pk_mul_f32 v[28:29], v[28:29], v[44:45] op_sel_hi:[1,0]
	v_pk_mul_f32 v[26:27], v[26:27], v[44:45] op_sel_hi:[1,0]
	v_pk_mul_f32 v[24:25], v[24:25], v[44:45] op_sel_hi:[1,0]
	v_pk_mul_f32 v[22:23], v[22:23], v[44:45] op_sel_hi:[1,0]
	v_pk_mul_f32 v[20:21], v[20:21], v[44:45] op_sel_hi:[1,0]
	v_pk_mul_f32 v[18:19], v[18:19], v[44:45] op_sel_hi:[1,0]
	v_pk_mul_f32 v[16:17], v[16:17], v[44:45] op_sel_hi:[1,0]
	v_pk_mul_f32 v[14:15], v[14:15], v[44:45] op_sel_hi:[1,0]
	v_pk_mul_f32 v[12:13], v[12:13], v[44:45] op_sel_hi:[1,0]
	v_pk_mul_f32 v[10:11], v[10:11], v[44:45] op_sel_hi:[1,0]
	v_pk_mul_f32 v[8:9], v[8:9], v[44:45] op_sel_hi:[1,0]
	v_pk_mul_f32 v[6:7], v[6:7], v[44:45] op_sel_hi:[1,0]
	v_pk_mul_f32 v[4:5], v[4:5], v[44:45] op_sel_hi:[1,0]
	v_pk_mul_f32 v[2:3], v[2:3], v[44:45] op_sel_hi:[1,0]
	v_fmac_f32_e32 v65, v130, v44
	v_cvt_pk_bf16_f32 v47, v39, v48
	v_cvt_pk_bf16_f32 v48, v49, v50
	v_cvt_pk_bf16_f32 v49, v43, v58
	v_add3_u32 v43, s81, v134, v101
	v_cvt_pk_bf16_f32 v46, v37, v38
	v_cvt_pk_bf16_f32 v38, v89, v34
	v_cvt_pk_bf16_f32 v39, v90, v40
	v_cvt_pk_bf16_f32 v40, v41, v52
	v_cvt_pk_bf16_f32 v41, v53, v54
	v_cvt_pk_bf16_f32 v34, v55, v56
	v_add3_u32 v56, s81, v135, v101
	ds_read_b64_tr_b16 v[52:53], v43
	v_add3_u32 v43, s81, v133, v101
	v_cvt_pk_bf16_f32 v45, v35, v36
	v_cvt_pk_bf16_f32 v35, v57, v60
	ds_read_b64_tr_b16 v[54:55], v43
	ds_read_b64_tr_b16 v[56:57], v56
	v_add3_u32 v43, s81, v132, v101
	v_cvt_pk_bf16_f32 v36, v59, v64
	ds_read_b64_tr_b16 v[58:59], v43
	v_cvt_pk_bf16_f32 v44, v88, v66
	v_add3_u32 v43, s81, v129, v101
	v_cvt_pk_bf16_f32 v50, v51, v62
	s_waitcnt lgkmcnt(2)
	v_mfma_f32_32x32x16_bf16 v[18:33], v[52:55], v[44:47], v[18:33]
	v_cvt_pk_bf16_f32 v51, v61, v84
	v_cvt_pk_bf16_f32 v37, v63, v86
	v_mov_b32_e32 v130, v65
	v_mov_b32_e32 v131, v42
	s_waitcnt lgkmcnt(0)
	v_mfma_f32_32x32x16_bf16 v[2:17], v[56:59], v[44:47], v[2:17]
	ds_read_b64_tr_b16 v[44:45], v43
	v_add3_u32 v43, s81, v128, v101
	ds_read_b64_tr_b16 v[46:47], v43
	v_add3_u32 v43, s81, v127, v101
	ds_read_b64_tr_b16 v[52:53], v43
	v_add3_u32 v43, s81, v126, v101
	ds_read_b64_tr_b16 v[54:55], v43
	v_add3_u32 v43, s81, v125, v101
	s_waitcnt lgkmcnt(2)
	v_mfma_f32_32x32x16_bf16 v[18:33], v[44:47], v[48:51], v[18:33]
	ds_read_b64_tr_b16 v[44:45], v43
	v_add3_u32 v43, s81, v124, v101
	ds_read_b64_tr_b16 v[46:47], v43
	v_add3_u32 v43, s81, v123, v101
	s_waitcnt lgkmcnt(2)
	v_mfma_f32_32x32x16_bf16 v[2:17], v[52:55], v[48:51], v[2:17]
	ds_read_b64_tr_b16 v[48:49], v43
	v_add3_u32 v43, s81, v122, v101
	ds_read_b64_tr_b16 v[50:51], v43
	v_add3_u32 v43, s81, v119, v101
	s_waitcnt lgkmcnt(2)
	v_mfma_f32_32x32x16_bf16 v[18:33], v[44:47], v[38:41], v[18:33]
	ds_read_b64_tr_b16 v[44:45], v43
	v_add3_u32 v43, s81, v118, v101
	ds_read_b64_tr_b16 v[46:47], v43
	s_waitcnt lgkmcnt(2)
	v_mfma_f32_32x32x16_bf16 v[2:17], v[48:51], v[38:41], v[2:17]
	v_add3_u32 v38, s81, v121, v101
	v_add3_u32 v40, s81, v120, v101
	ds_read_b64_tr_b16 v[38:39], v38
	ds_read_b64_tr_b16 v[40:41], v40
	s_waitcnt lgkmcnt(0)
	v_mfma_f32_32x32x16_bf16 v[18:33], v[38:41], v[34:37], v[18:33]
	v_mfma_f32_32x32x16_bf16 v[2:17], v[44:47], v[34:37], v[2:17]

; #define PG8_STAGE(bufoff, gbase, voff) do { _Pragma("unroll") for (int _i = 0; _i < 2; ++_i) \
;         __builtin_amdgcn_global_load_lds((const unsigned*)((const char*)(gbase) + (voff)[_i]), (PG8_LAS unsigned*)(lds + (bufoff) + ldsw + _i * 8192), 16, 0, 0); } while (0)
; #define PG8_LDA(dst, b, h) do { _Pragma("unroll") for (int m = 0; m < 4; ++m) _Pragma("unroll") for (int k = 0; k < 2; ++k) dst[m][k] = *(const PG8_LAS bf16x8*)(lds + PG8_SA(b, h) + aoff + m * 2048 + k * 1024); } while (0)
; #define PG8_LDB(dst, b, h) do { _Pragma("unroll") for (int n = 0; n < 2; ++n) _Pragma("unroll") for (int k = 0; k < 2; ++k) dst[n][k] = *(const PG8_LAS bf16x8*)(lds + PG8_SB(b, h) + boff + n * 2048 + k * 1024); } while (0)
; #define PG8_MMA(ai, bj, At, Bt) do { __builtin_amdgcn_s_setprio(1); _Pragma("unroll") for (int m = 0; m < 4; ++m) _Pragma("unroll") for (int n = 0; n < 2; ++n) _Pragma("unroll") for (int k = 0; k < 2; ++k) \
;         acc[ai][bj][m][n] = __builtin_amdgcn_mfma_f32_16x16x32_bf16(Bt[n][k], At[m][k], acc[ai][bj][m][n], 0, 0, 0); __builtin_amdgcn_s_setprio(0); } while (0)
; #define PG8_WAIT_V(n) asm volatile("s_waitcnt vmcnt(" #n ")" ::: "memory")
; #define PG8_BAR __builtin_amdgcn_s_barrier()
; template <class Epi, class Sched, bool ALIGN_EPI = false, bool SP2 = false>
; __device__ __forceinline__ void gemm_phase(PG8_LAS unsigned char* lds, const Gemm g, const Sched& S, const Epi& E) {
;     ...
;         for (int t = 0; t < nt; t += 2) {
;             const bool last = (t == nt - 2);
;             const char* a1 = cA + (size_t)(t + 1) * kstep;
;             const char* a2 = last ? nA : cA + (size_t)(t + 2) * kstep; const char* b2 = last ? nB : cB + (size_t)(t + 2) * kstep;
;             const char* a3 = a2 + kstep; const char* b3 = b2 + kstep;
;             if (last && has_next) S.a_ready(nxt);
;             if constexpr (SP2) {
;             PG8_LDB(B0, 0, 0); PG8_LDB(B1, 0, 1); PG8_SCHED; PG8_LDA(At, 0, 0); PG8_STAGE(PG8_SA(1, 1), a1 + hstep, voffA);
;             PG8_WAIT_V(8); PG8_WAIT_L(0); PG8_BAR; PG8_MMA(0, 0, At, B0); PG8_MMA(0, 1, At, B1); PG8_BAR; PG8_SCHED;
;             PG8_LDA(At, 0, 1); PG8_STAGE(PG8_SB(0, 0), b2, voffB); PG8_STAGE(PG8_SB(0, 1), b2 + hstep, voffB); PG8_STAGE(PG8_SA(0, 0), a2, voffA);
;             PG8_WAIT_V(8); PG8_WAIT_L(0); PG8_BAR; PG8_MMA(1, 0, At, B0); PG8_MMA(1, 1, At, B1); PG8_BAR; PG8_SCHED;
.LBB0_782:
	s_add_u32 s1, s26, 0xfff80080
	s_addc_u32 s2, s27, -1
	s_add_i32 s3, 0, 0x10000
	s_cmpk_eq_i32 s28, 0x1e00
	s_cselect_b32 s35, s21, s2
	s_cselect_b32 s34, s50, s1
	v_add_u32_e32 v66, s3, v206
	s_cselect_b32 s31, s19, s53
	s_cselect_b32 s30, s51, s52
	s_add_i32 s1, 0, 0x14000
	ds_read_b128 v[152:155], v66
	ds_read_b128 v[156:159], v66 offset:1024
	ds_read_b128 v[160:163], v66 offset:2048
	ds_read_b128 v[164:167], v66 offset:3072
	v_add_u32_e32 v66, s1, v206
	ds_read_b128 v[168:171], v66
	ds_read_b128 v[172:175], v66 offset:1024
	ds_read_b128 v[176:179], v66 offset:2048
	ds_read_b128 v[180:183], v66 offset:3072
	v_lshl_add_u64 v[68:69], s[26:27], 0, v[142:143]
	s_add_i32 m0, s43, 0xc000
	ds_read_b128 v[184:187], v208
	ds_read_b128 v[188:191], v208 offset:1024
	ds_read_b128 v[192:195], v208 offset:2048
	ds_read_b128 v[196:199], v208 offset:3072
	ds_read_b128 v[200:203], v208 offset:4096
	ds_read_b128 v[220:223], v208 offset:5120
	ds_read_b128 v[224:227], v208 offset:6144
	ds_read_b128 v[228:231], v208 offset:7168
	global_load_lds_dwordx4 v[68:69], off
	v_lshl_add_u64 v[68:69], s[26:27], 0, v[144:145]
	s_add_i32 m0, s43, 0xe000
	s_nop 0
	global_load_lds_dwordx4 v[68:69], off
	s_waitcnt vmcnt(8)
	s_waitcnt lgkmcnt(0)
	s_barrier
	s_setprio 1
	s_waitcnt lgkmcnt(0)
	v_mfma_f32_16x16x32_bf16 v[130:133], v[152:155], v[184:187], v[130:133]
	v_mfma_f32_16x16x32_bf16 v[126:129], v[160:163], v[184:187], v[126:129]
	v_mfma_f32_16x16x32_bf16 v[114:117], v[152:155], v[192:195], v[114:117]
	v_mfma_f32_16x16x32_bf16 v[110:113], v[160:163], v[192:195], v[110:113]
	v_mfma_f32_16x16x32_bf16 v[98:101], v[152:155], v[200:203], v[98:101]
	v_mfma_f32_16x16x32_bf16 v[94:97], v[160:163], v[200:203], v[94:97]
	v_mfma_f32_16x16x32_bf16 v[82:85], v[152:155], v[224:227], v[82:85]
	v_mfma_f32_16x16x32_bf16 v[78:81], v[160:163], v[224:227], v[78:81]
	v_mfma_f32_16x16x32_bf16 v[130:133], v[156:159], v[188:191], v[130:133]
	v_mfma_f32_16x16x32_bf16 v[126:129], v[164:167], v[188:191], v[126:129]
	v_mfma_f32_16x16x32_bf16 v[114:117], v[156:159], v[196:199], v[114:117]
	v_mfma_f32_16x16x32_bf16 v[110:113], v[164:167], v[196:199], v[110:113]
	v_mfma_f32_16x16x32_bf16 v[98:101], v[156:159], v[220:223], v[98:101]
	v_mfma_f32_16x16x32_bf16 v[94:97], v[164:167], v[220:223], v[94:97]
	v_mfma_f32_16x16x32_bf16 v[82:85], v[156:159], v[228:231], v[82:85]
	v_mfma_f32_16x16x32_bf16 v[78:81], v[164:167], v[228:231], v[78:81]
	s_setprio 0
	s_setprio 1
	v_mfma_f32_16x16x32_bf16 v[122:125], v[168:171], v[184:187], v[122:125]
	v_mfma_f32_16x16x32_bf16 v[118:121], v[176:179], v[184:187], v[118:121]
	v_mfma_f32_16x16x32_bf16 v[106:109], v[168:171], v[192:195], v[106:109]
	v_mfma_f32_16x16x32_bf16 v[102:105], v[176:179], v[192:195], v[102:105]
	v_mfma_f32_16x16x32_bf16 v[90:93], v[168:171], v[200:203], v[90:93]
	v_mfma_f32_16x16x32_bf16 v[86:89], v[176:179], v[200:203], v[86:89]
	v_mfma_f32_16x16x32_bf16 v[74:77], v[168:171], v[224:227], v[74:77]
	v_mfma_f32_16x16x32_bf16 v[68:71], v[176:179], v[224:227], v[70:73]
	v_mfma_f32_16x16x32_bf16 v[122:125], v[172:175], v[188:191], v[122:125]
	v_mfma_f32_16x16x32_bf16 v[118:121], v[180:183], v[188:191], v[118:121]
	v_mfma_f32_16x16x32_bf16 v[106:109], v[172:175], v[196:199], v[106:109]
	v_mfma_f32_16x16x32_bf16 v[102:105], v[180:183], v[196:199], v[102:105]
	v_mfma_f32_16x16x32_bf16 v[90:93], v[172:175], v[220:223], v[90:93]
	v_mfma_f32_16x16x32_bf16 v[86:89], v[180:183], v[220:223], v[86:89]
	v_mfma_f32_16x16x32_bf16 v[74:77], v[172:175], v[228:231], v[74:77]
	v_mfma_f32_16x16x32_bf16 v[68:71], v[180:183], v[228:231], v[68:71]
	s_setprio 0
	s_barrier
	s_add_i32 s2, s3, s42
	v_lshl_add_u64 v[204:205], s[30:31], 0, v[138:139]
	s_mov_b32 m0, s2
	ds_read_b128 v[184:187], v208 offset:16384
	ds_read_b128 v[188:191], v208 offset:17408
	ds_read_b128 v[192:195], v208 offset:18432
	ds_read_b128 v[196:199], v208 offset:19456
	ds_read_b128 v[200:203], v208 offset:20480
	ds_read_b128 v[220:223], v208 offset:21504
	ds_read_b128 v[224:227], v208 offset:22528
	ds_read_b128 v[228:231], v208 offset:23552
	global_load_lds_dwordx4 v[204:205], off
	s_add_i32 m0, s2, 0x2000
	s_add_u32 s2, s30, 0x80000
	v_lshl_add_u64 v[210:211], s[30:31], 0, v[134:135]
	s_addc_u32 s3, s31, 0
	s_add_i32 s1, s1, s42
	global_load_lds_dwordx4 v[210:211], off
	v_lshl_add_u64 v[72:73], s[2:3], 0, v[138:139]
	s_mov_b32 m0, s1
	v_lshl_add_u64 v[232:233], s[34:35], 0, v[140:141]
	global_load_lds_dwordx4 v[72:73], off
	v_lshl_add_u64 v[72:73], s[2:3], 0, v[134:135]
	s_add_i32 m0, s1, 0x2000
	v_lshl_add_u64 v[234:235], s[34:35], 0, v[136:137]
	global_load_lds_dwordx4 v[72:73], off
	s_mov_b32 m0, s43
	s_nop 0
	global_load_lds_dwordx4 v[232:233], off
	s_mov_b32 m0, s44
	s_nop 0
	global_load_lds_dwordx4 v[234:235], off
	s_waitcnt vmcnt(8)
	s_waitcnt lgkmcnt(0)
	s_barrier
; #define PG8_STAGE(bufoff, gbase, voff) do { _Pragma("unroll") for (int _i = 0; _i < 2; ++_i) \
;         __builtin_amdgcn_global_load_lds((const unsigned*)((const char*)(gbase) + (voff)[_i]), (PG8_LAS unsigned*)(lds + (bufoff) + ldsw + _i * 8192), 16, 0, 0); } while (0)
; #define PG8_LDA(dst, b, h) do { _Pragma("unroll") for (int m = 0; m < 4; ++m) _Pragma("unroll") for (int k = 0; k < 2; ++k) dst[m][k] = *(const PG8_LAS bf16x8*)(lds + PG8_SA(b, h) + aoff + m * 2048 + k * 1024); } while (0)
; #define PG8_LDB(dst, b, h) do { _Pragma("unroll") for (int n = 0; n < 2; ++n) _Pragma("unroll") for (int k = 0; k < 2; ++k) dst[n][k] = *(const PG8_LAS bf16x8*)(lds + PG8_SB(b, h) + boff + n * 2048 + k * 1024); } while (0)
; #define PG8_MMA(ai, bj, At, Bt) do { __builtin_amdgcn_s_setprio(1); _Pragma("unroll") for (int m = 0; m < 4; ++m) _Pragma("unroll") for (int n = 0; n < 2; ++n) _Pragma("unroll") for (int k = 0; k < 2; ++k) \
;         acc[ai][bj][m][n] = __builtin_amdgcn_mfma_f32_16x16x32_bf16(Bt[n][k], At[m][k], acc[ai][bj][m][n], 0, 0, 0); __builtin_amdgcn_s_setprio(0); } while (0)
; #define PG8_WAIT_V(n) asm volatile("s_waitcnt vmcnt(" #n ")" ::: "memory")
; #define PG8_WAIT_L(n) asm volatile("s_waitcnt lgkmcnt(" #n ")" ::: "memory")
; #define PG8_BAR __builtin_amdgcn_s_barrier()
; #define PG8_SCHED __builtin_amdgcn_sched_barrier(0)
; template <class Epi, class Sched, bool ALIGN_EPI = false, bool SP2 = false>
; __device__ __forceinline__ void gemm_phase(PG8_LAS unsigned char* lds, const Gemm g, const Sched& S, const Epi& E) {
;     ...
;             PG8_WAIT_V(8); PG8_WAIT_L(0); PG8_BAR; PG8_MMA(1, 0, At, B0); PG8_MMA(1, 1, At, B1); PG8_BAR; PG8_SCHED;
;             PG8_LDB(B0, 1, 0); PG8_LDB(B1, 1, 1); PG8_SCHED; PG8_LDA(At, 1, 0); PG8_STAGE(PG8_SA(0, 1), a2 + hstep, voffA);
;             PG8_WAIT_V(8); PG8_WAIT_L(0); PG8_BAR; PG8_MMA(0, 0, At, B0); PG8_MMA(0, 1, At, B1); PG8_BAR; PG8_SCHED;
	s_setprio 1
	s_waitcnt lgkmcnt(0)
	v_mfma_f32_16x16x32_bf16 v[62:65], v[152:155], v[184:187], v[62:65]
	v_mfma_f32_16x16x32_bf16 v[58:61], v[160:163], v[184:187], v[58:61]
	v_mfma_f32_16x16x32_bf16 v[46:49], v[152:155], v[192:195], v[46:49]
	v_mfma_f32_16x16x32_bf16 v[42:45], v[160:163], v[192:195], v[42:45]
	v_mfma_f32_16x16x32_bf16 v[30:33], v[152:155], v[200:203], v[30:33]
	v_mfma_f32_16x16x32_bf16 v[26:29], v[160:163], v[200:203], v[26:29]
	v_mfma_f32_16x16x32_bf16 v[14:17], v[152:155], v[224:227], v[14:17]
	v_mfma_f32_16x16x32_bf16 v[10:13], v[160:163], v[224:227], v[10:13]
	v_mfma_f32_16x16x32_bf16 v[62:65], v[156:159], v[188:191], v[62:65]
	v_mfma_f32_16x16x32_bf16 v[58:61], v[164:167], v[188:191], v[58:61]
	v_mfma_f32_16x16x32_bf16 v[46:49], v[156:159], v[196:199], v[46:49]
	v_mfma_f32_16x16x32_bf16 v[42:45], v[164:167], v[196:199], v[42:45]
	v_mfma_f32_16x16x32_bf16 v[30:33], v[156:159], v[220:223], v[30:33]
	v_mfma_f32_16x16x32_bf16 v[26:29], v[164:167], v[220:223], v[26:29]
	v_mfma_f32_16x16x32_bf16 v[14:17], v[156:159], v[228:231], v[14:17]
	v_mfma_f32_16x16x32_bf16 v[10:13], v[164:167], v[228:231], v[10:13]
	s_setprio 0
	s_setprio 1
	v_mfma_f32_16x16x32_bf16 v[54:57], v[168:171], v[184:187], v[54:57]
	v_mfma_f32_16x16x32_bf16 v[50:53], v[176:179], v[184:187], v[50:53]
	v_mfma_f32_16x16x32_bf16 v[38:41], v[168:171], v[192:195], v[38:41]
	v_mfma_f32_16x16x32_bf16 v[34:37], v[176:179], v[192:195], v[34:37]
	v_mfma_f32_16x16x32_bf16 v[22:25], v[168:171], v[200:203], v[22:25]
	v_mfma_f32_16x16x32_bf16 v[18:21], v[176:179], v[200:203], v[18:21]
	v_mfma_f32_16x16x32_bf16 v[6:9], v[168:171], v[224:227], v[6:9]
	v_mfma_f32_16x16x32_bf16 v[2:5], v[176:179], v[224:227], v[2:5]
	v_mfma_f32_16x16x32_bf16 v[54:57], v[172:175], v[188:191], v[54:57]
	v_mfma_f32_16x16x32_bf16 v[50:53], v[180:183], v[188:191], v[50:53]
	v_mfma_f32_16x16x32_bf16 v[38:41], v[172:175], v[196:199], v[38:41]
	v_mfma_f32_16x16x32_bf16 v[34:37], v[180:183], v[196:199], v[34:37]
	v_mfma_f32_16x16x32_bf16 v[22:25], v[172:175], v[220:223], v[22:25]
	v_mfma_f32_16x16x32_bf16 v[18:21], v[180:183], v[220:223], v[18:21]
	v_mfma_f32_16x16x32_bf16 v[6:9], v[172:175], v[228:231], v[6:9]
	v_mfma_f32_16x16x32_bf16 v[2:5], v[180:183], v[228:231], v[2:5]
	s_setprio 0
	s_barrier
	s_add_i32 s1, 0, 0x18000
	v_add_u32_e32 v66, s1, v206
	s_add_i32 s55, 0, 0x1c000
	ds_read_b128 v[152:155], v66
	ds_read_b128 v[156:159], v66 offset:1024
	ds_read_b128 v[160:163], v66 offset:2048
	ds_read_b128 v[164:167], v66 offset:3072
	v_add_u32_e32 v66, s55, v206
	ds_read_b128 v[168:171], v66
	ds_read_b128 v[172:175], v66 offset:1024
	ds_read_b128 v[176:179], v66 offset:2048
	ds_read_b128 v[180:183], v66 offset:3072
	s_add_u32 s2, s34, 0x80000
	s_addc_u32 s3, s35, 0
	s_mov_b32 m0, s45
	v_lshl_add_u64 v[72:73], s[2:3], 0, v[140:141]
	ds_read_b128 v[184:187], v208 offset:32768
	ds_read_b128 v[188:191], v208 offset:33792
	ds_read_b128 v[192:195], v208 offset:34816
	ds_read_b128 v[196:199], v208 offset:35840
	ds_read_b128 v[200:203], v208 offset:36864
	ds_read_b128 v[220:223], v208 offset:37888
	ds_read_b128 v[224:227], v208 offset:38912
	ds_read_b128 v[228:231], v208 offset:39936
	global_load_lds_dwordx4 v[72:73], off
	v_lshl_add_u64 v[72:73], s[2:3], 0, v[136:137]
	s_mov_b32 m0, s46
	s_nop 0
	global_load_lds_dwordx4 v[72:73], off
	s_waitcnt vmcnt(8)
	s_waitcnt lgkmcnt(0)
	s_barrier
	s_setprio 1
	s_waitcnt lgkmcnt(0)
	v_mfma_f32_16x16x32_bf16 v[130:133], v[152:155], v[184:187], v[130:133]
	v_mfma_f32_16x16x32_bf16 v[126:129], v[160:163], v[184:187], v[126:129]
	v_mfma_f32_16x16x32_bf16 v[114:117], v[152:155], v[192:195], v[114:117]
	v_mfma_f32_16x16x32_bf16 v[110:113], v[160:163], v[192:195], v[110:113]
	v_mfma_f32_16x16x32_bf16 v[98:101], v[152:155], v[200:203], v[98:101]
	v_mfma_f32_16x16x32_bf16 v[94:97], v[160:163], v[200:203], v[94:97]
	v_mfma_f32_16x16x32_bf16 v[82:85], v[152:155], v[224:227], v[82:85]
	v_mfma_f32_16x16x32_bf16 v[78:81], v[160:163], v[224:227], v[78:81]
	v_mfma_f32_16x16x32_bf16 v[130:133], v[156:159], v[188:191], v[130:133]
	v_mfma_f32_16x16x32_bf16 v[126:129], v[164:167], v[188:191], v[126:129]
	v_mfma_f32_16x16x32_bf16 v[114:117], v[156:159], v[196:199], v[114:117]
	v_mfma_f32_16x16x32_bf16 v[110:113], v[164:167], v[196:199], v[110:113]
	v_mfma_f32_16x16x32_bf16 v[98:101], v[156:159], v[220:223], v[98:101]
	v_mfma_f32_16x16x32_bf16 v[94:97], v[164:167], v[220:223], v[94:97]
	v_mfma_f32_16x16x32_bf16 v[82:85], v[156:159], v[228:231], v[82:85]
	v_mfma_f32_16x16x32_bf16 v[78:81], v[164:167], v[228:231], v[78:81]
	s_setprio 0
	s_setprio 1
	v_mfma_f32_16x16x32_bf16 v[122:125], v[168:171], v[184:187], v[122:125]
	v_mfma_f32_16x16x32_bf16 v[118:121], v[176:179], v[184:187], v[118:121]
	v_mfma_f32_16x16x32_bf16 v[106:109], v[168:171], v[192:195], v[106:109]
	v_mfma_f32_16x16x32_bf16 v[102:105], v[176:179], v[192:195], v[102:105]
	v_mfma_f32_16x16x32_bf16 v[90:93], v[168:171], v[200:203], v[90:93]
	v_mfma_f32_16x16x32_bf16 v[86:89], v[176:179], v[200:203], v[86:89]
	v_mfma_f32_16x16x32_bf16 v[72:75], v[168:171], v[224:227], v[74:77]
	v_mfma_f32_16x16x32_bf16 v[68:71], v[176:179], v[224:227], v[68:71]
	v_mfma_f32_16x16x32_bf16 v[122:125], v[172:175], v[188:191], v[122:125]
	v_mfma_f32_16x16x32_bf16 v[118:121], v[180:183], v[188:191], v[118:121]
	v_mfma_f32_16x16x32_bf16 v[106:109], v[172:175], v[196:199], v[106:109]
	v_mfma_f32_16x16x32_bf16 v[102:105], v[180:183], v[196:199], v[102:105]
	v_mfma_f32_16x16x32_bf16 v[90:93], v[172:175], v[220:223], v[90:93]
	v_mfma_f32_16x16x32_bf16 v[86:89], v[180:183], v[220:223], v[86:89]
	v_mfma_f32_16x16x32_bf16 v[74:77], v[172:175], v[228:231], v[72:75]
	v_mfma_f32_16x16x32_bf16 v[70:73], v[180:183], v[228:231], v[68:71]
	s_setprio 0
	s_barrier
; #define PG8_STAGE(bufoff, gbase, voff) do { _Pragma("unroll") for (int _i = 0; _i < 2; ++_i) \
;         __builtin_amdgcn_global_load_lds((const unsigned*)((const char*)(gbase) + (voff)[_i]), (PG8_LAS unsigned*)(lds + (bufoff) + ldsw + _i * 8192), 16, 0, 0); } while (0)
; #define PG8_LDA(dst, b, h) do { _Pragma("unroll") for (int m = 0; m < 4; ++m) _Pragma("unroll") for (int k = 0; k < 2; ++k) dst[m][k] = *(const PG8_LAS bf16x8*)(lds + PG8_SA(b, h) + aoff + m * 2048 + k * 1024); } while (0)
; #define PG8_MMA(ai, bj, At, Bt) do { __builtin_amdgcn_s_setprio(1); _Pragma("unroll") for (int m = 0; m < 4; ++m) _Pragma("unroll") for (int n = 0; n < 2; ++n) _Pragma("unroll") for (int k = 0; k < 2; ++k) \
;         acc[ai][bj][m][n] = __builtin_amdgcn_mfma_f32_16x16x32_bf16(Bt[n][k], At[m][k], acc[ai][bj][m][n], 0, 0, 0); __builtin_amdgcn_s_setprio(0); } while (0)
; #define PG8_WAIT_V(n) asm volatile("s_waitcnt vmcnt(" #n ")" ::: "memory")
; #define PG8_WAIT_L(n) asm volatile("s_waitcnt lgkmcnt(" #n ")" ::: "memory")
; #define PG8_BAR __builtin_amdgcn_s_barrier()
; #define PG8_SCHED __builtin_amdgcn_sched_barrier(0)
;     __device__ __forceinline__ void mid(f32x4 (&acc)[2][2][4][2], const Unit& u, int seg, int wr, int wc, int fr, int fq) const {
;     ...
;         for (int ai = 0; ai < 2; ++ai)
; #pragma unroll
;             for (int m = 0; m < 4; ++m) { const unsigned char* rowp = G + (size_t)(row0 + ai * HALF + m * 16) * 8192 + col0 + seg * 2048;
; #pragma unroll
;                 for (int bj = 0; bj < 2; ++bj) { ga[ai][m][bj] = *(const u32x2v*)(rowp + bj * HALF); gb[ai][m][bj] = *(const u32x2v*)(rowp + 2048 + bj * HALF); } }
; template <class Epi, class Sched, bool ALIGN_EPI = false, bool SP2 = false>
; __device__ __forceinline__ void gemm_phase(PG8_LAS unsigned char* lds, const Gemm g, const Sched& S, const Epi& E) {
;     ...
;             PG8_LDA(At, 1, 1); PG8_STAGE(PG8_SB(1, 0), b3, voffB); PG8_STAGE(PG8_SB(1, 1), b3 + hstep, voffB); PG8_STAGE(PG8_SA(1, 0), a3, voffA);
;             PG8_WAIT_V(8); PG8_WAIT_L(0); PG8_BAR; PG8_MMA(1, 0, At, B0); PG8_MMA(1, 1, At, B1); PG8_BAR; PG8_SCHED;
	s_add_i32 s1, s1, s42
	v_lshl_add_u64 v[68:69], v[204:205], 0, s[88:89]
	s_mov_b32 m0, s1
	ds_read_b128 v[184:187], v208 offset:49152
	ds_read_b128 v[188:191], v208 offset:50176
	ds_read_b128 v[192:195], v208 offset:51200
	ds_read_b128 v[196:199], v208 offset:52224
	ds_read_b128 v[200:203], v208 offset:53248
	ds_read_b128 v[220:223], v208 offset:54272
	ds_read_b128 v[224:227], v208 offset:55296
	ds_read_b128 v[228:231], v208 offset:56320
	global_load_lds_dwordx4 v[68:69], off
	s_add_i32 m0, s1, 0x2000
	s_add_u32 s2, s30, 0x80080
	v_lshl_add_u64 v[68:69], v[210:211], 0, s[88:89]
	s_addc_u32 s3, s31, 0
	s_add_i32 s1, s55, s42
	global_load_lds_dwordx4 v[68:69], off
	v_lshl_add_u64 v[68:69], s[2:3], 0, v[138:139]
	s_mov_b32 m0, s1
	s_nop 0
	global_load_lds_dwordx4 v[68:69], off
	v_lshl_add_u64 v[68:69], s[2:3], 0, v[134:135]
	s_add_i32 m0, s1, 0x2000
	s_nop 0
	global_load_lds_dwordx4 v[68:69], off
	v_lshl_add_u64 v[68:69], v[232:233], 0, s[88:89]
	s_mov_b32 m0, s47
	s_nop 0
	global_load_lds_dwordx4 v[68:69], off
	v_lshl_add_u64 v[68:69], v[234:235], 0, s[88:89]
	s_mov_b32 m0, s48
	s_nop 0
	global_load_lds_dwordx4 v[68:69], off
	s_waitcnt vmcnt(8)
	s_waitcnt lgkmcnt(0)
	s_barrier
	s_setprio 1
	s_waitcnt lgkmcnt(0)
	v_mfma_f32_16x16x32_bf16 v[62:65], v[152:155], v[184:187], v[62:65]
	v_mfma_f32_16x16x32_bf16 v[58:61], v[160:163], v[184:187], v[58:61]
	v_mfma_f32_16x16x32_bf16 v[46:49], v[152:155], v[192:195], v[46:49]
	v_mfma_f32_16x16x32_bf16 v[42:45], v[160:163], v[192:195], v[42:45]
	v_mfma_f32_16x16x32_bf16 v[30:33], v[152:155], v[200:203], v[30:33]
	v_mfma_f32_16x16x32_bf16 v[26:29], v[160:163], v[200:203], v[26:29]
	v_mfma_f32_16x16x32_bf16 v[14:17], v[152:155], v[224:227], v[14:17]
	v_mfma_f32_16x16x32_bf16 v[10:13], v[160:163], v[224:227], v[10:13]
	v_mfma_f32_16x16x32_bf16 v[62:65], v[156:159], v[188:191], v[62:65]
	v_mfma_f32_16x16x32_bf16 v[58:61], v[164:167], v[188:191], v[58:61]
	v_mfma_f32_16x16x32_bf16 v[46:49], v[156:159], v[196:199], v[46:49]
	v_mfma_f32_16x16x32_bf16 v[42:45], v[164:167], v[196:199], v[42:45]
	v_mfma_f32_16x16x32_bf16 v[30:33], v[156:159], v[220:223], v[30:33]
	v_mfma_f32_16x16x32_bf16 v[26:29], v[164:167], v[220:223], v[26:29]
	v_mfma_f32_16x16x32_bf16 v[14:17], v[156:159], v[228:231], v[14:17]
	v_mfma_f32_16x16x32_bf16 v[10:13], v[164:167], v[228:231], v[10:13]
	s_setprio 0
	s_setprio 1
	v_mfma_f32_16x16x32_bf16 v[54:57], v[168:171], v[184:187], v[54:57]
	v_mfma_f32_16x16x32_bf16 v[50:53], v[176:179], v[184:187], v[50:53]
	v_mfma_f32_16x16x32_bf16 v[38:41], v[168:171], v[192:195], v[38:41]
	v_mfma_f32_16x16x32_bf16 v[34:37], v[176:179], v[192:195], v[34:37]
	v_mfma_f32_16x16x32_bf16 v[22:25], v[168:171], v[200:203], v[22:25]
	v_mfma_f32_16x16x32_bf16 v[18:21], v[176:179], v[200:203], v[18:21]
	v_mfma_f32_16x16x32_bf16 v[6:9], v[168:171], v[224:227], v[6:9]
	v_mfma_f32_16x16x32_bf16 v[2:5], v[176:179], v[224:227], v[2:5]
	v_mfma_f32_16x16x32_bf16 v[54:57], v[172:175], v[188:191], v[54:57]
	v_mfma_f32_16x16x32_bf16 v[50:53], v[180:183], v[188:191], v[50:53]
	v_mfma_f32_16x16x32_bf16 v[38:41], v[172:175], v[196:199], v[38:41]
	v_mfma_f32_16x16x32_bf16 v[34:37], v[180:183], v[196:199], v[34:37]
	v_mfma_f32_16x16x32_bf16 v[22:25], v[172:175], v[220:223], v[22:25]
	v_mfma_f32_16x16x32_bf16 v[18:21], v[180:183], v[220:223], v[18:21]
	v_mfma_f32_16x16x32_bf16 v[6:9], v[172:175], v[228:231], v[6:9]
	v_mfma_f32_16x16x32_bf16 v[2:5], v[180:183], v[228:231], v[2:5]
	s_setprio 0
	s_barrier
	s_mov_b32 s1, s54
	s_add_i32 s54, s54, 2
	s_and_b32 s2, s54, 6
	s_cmp_eq_u32 s2, 0
	s_cselect_b64 s[2:3], -1, 0
	s_cmp_gt_u32 s1, 29
	s_cselect_b64 s[30:31], -1, 0
	s_cmp_lt_u32 s1, 30
	s_cselect_b64 s[34:35], -1, 0
	s_and_b64 s[2:3], s[2:3], s[34:35]
	s_andn2_b64 vcc, exec, s[2:3]
	s_cbranch_vccnz .LBB0_781
	v_mov_b32_e32 v68, v148
	s_nop 0
	v_ashrrev_i32_e32 v69, 31, v68
	v_lshlrev_b64 v[68:69], 13, v[68:69]
	v_lshl_add_u64 v[68:69], s[28:29], 0, v[68:69]
	v_lshl_add_u64 v[68:69], v[150:151], 0, v[68:69]
	v_add_co_u32_e32 v152, vcc, 0xcbff000, v68
	s_nop 1
	v_addc_co_u32_e32 v153, vcc, 0, v69, vcc
	v_add_co_u32_e32 v154, vcc, 0xcc00000, v68
	s_nop 1
	v_addc_co_u32_e32 v155, vcc, 0, v69, vcc
	global_load_dwordx2 v[210:211], v[152:153], off offset:2560
	global_load_dwordx2 v[220:221], v[154:155], off offset:512
	global_load_dwordx2 v[222:223], v[154:155], off offset:640
	global_load_dwordx2 v[224:225], v[152:153], off offset:2688
	v_add_co_u32_e32 v152, vcc, 0xcc1f000, v68
	s_nop 1
	v_addc_co_u32_e32 v153, vcc, 0, v69, vcc
	v_add_co_u32_e32 v154, vcc, 0xcc20000, v68
	s_nop 0
	s_nop 0
	v_addc_co_u32_e32 v155, vcc, 0, v69, vcc
	global_load_dwordx2 v[202:203], v[152:153], off offset:2560
	global_load_dwordx2 v[204:205], v[154:155], off offset:512
	global_load_dwordx2 v[200:201], v[154:155], off offset:640
	global_load_dwordx2 v[198:199], v[152:153], off offset:2688
	v_add_co_u32_e32 v152, vcc, 0xcc3f000, v68
	s_nop 0
	s_nop 0
	v_addc_co_u32_e32 v153, vcc, 0, v69, vcc
	v_add_co_u32_e32 v154, vcc, 0xcc40000, v68
	s_nop 0
	s_nop 0
	v_addc_co_u32_e32 v155, vcc, 0, v69, vcc
	global_load_dwordx2 v[194:195], v[152:153], off offset:2560
	global_load_dwordx2 v[196:197], v[154:155], off offset:512
	global_load_dwordx2 v[192:193], v[154:155], off offset:640
	global_load_dwordx2 v[190:191], v[152:153], off offset:2688
	v_add_co_u32_e32 v152, vcc, 0xcc5f000, v68
	s_nop 0
	s_nop 0
	v_addc_co_u32_e32 v153, vcc, 0, v69, vcc
	v_add_co_u32_e32 v154, vcc, 0xcc60000, v68
	s_nop 1
	v_addc_co_u32_e32 v155, vcc, 0, v69, vcc
	global_load_dwordx2 v[186:187], v[152:153], off offset:2560
	global_load_dwordx2 v[188:189], v[154:155], off offset:512
; __device__ __forceinline__ float gate_v(unsigned q) { return (float)q; }
;     __device__ __forceinline__ void mid(f32x4 (&acc)[2][2][4][2], const Unit& u, int seg, int wr, int wc, int fr, int fq) const {
;     ...
;         for (int ai = 0; ai < 2; ++ai)
; #pragma unroll
;             for (int m = 0; m < 4; ++m) { const unsigned char* rowp = G + (size_t)(row0 + ai * HALF + m * 16) * 8192 + col0 + seg * 2048;
; #pragma unroll
;                 for (int bj = 0; bj < 2; ++bj) { ga[ai][m][bj] = *(const u32x2v*)(rowp + bj * HALF); gb[ai][m][bj] = *(const u32x2v*)(rowp + 2048 + bj * HALF); } }
; #pragma unroll
;         for (int ai = 0; ai < 2; ++ai)
; #pragma unroll
;             for (int m = 0; m < 4; ++m)
; #pragma unroll
;                 for (int bj = 0; bj < 2; ++bj)
; #pragma unroll
;                     for (int e = 0; e < 8; ++e) { const unsigned a = (ga[ai][m][bj][e >> 2] >> (8 * (e & 3))) & 255u, b = (gb[ai][m][bj][e >> 2] >> (8 * (e & 3))) & 255u;
;                         acc[ai][bj][m][e >> 2][e & 3] *= gate_v(a) * __builtin_amdgcn_rcpf(gate_v(b)); }
	global_load_dwordx2 v[184:185], v[154:155], off offset:640
	global_load_dwordx2 v[182:183], v[152:153], off offset:2688
	v_add_co_u32_e32 v152, vcc, 0xccff000, v68
	s_nop 1
	v_addc_co_u32_e32 v153, vcc, 0, v69, vcc
	v_add_co_u32_e32 v154, vcc, 0xcd00000, v68
	s_nop 1
	v_addc_co_u32_e32 v155, vcc, 0, v69, vcc
	global_load_dwordx2 v[178:179], v[152:153], off offset:2560
	global_load_dwordx2 v[180:181], v[154:155], off offset:512
	global_load_dwordx2 v[176:177], v[154:155], off offset:640
	global_load_dwordx2 v[174:175], v[152:153], off offset:2688
	v_add_co_u32_e32 v152, vcc, 0xcd1f000, v68
	s_nop 1
	v_addc_co_u32_e32 v153, vcc, 0, v69, vcc
	v_add_co_u32_e32 v154, vcc, 0xcd20000, v68
	s_nop 1
	v_addc_co_u32_e32 v155, vcc, 0, v69, vcc
	global_load_dwordx2 v[170:171], v[152:153], off offset:2560
	global_load_dwordx2 v[172:173], v[154:155], off offset:512
	global_load_dwordx2 v[168:169], v[154:155], off offset:640
	global_load_dwordx2 v[166:167], v[152:153], off offset:2688
	v_add_co_u32_e32 v152, vcc, 0xcd3f000, v68
	s_nop 1
	v_addc_co_u32_e32 v153, vcc, 0, v69, vcc
	v_add_co_u32_e32 v154, vcc, 0xcd40000, v68
	s_nop 1
	v_addc_co_u32_e32 v155, vcc, 0, v69, vcc
	v_add_co_u32_e32 v226, vcc, 0xcd5f000, v68
	global_load_dwordx2 v[162:163], v[152:153], off offset:2560
	global_load_dwordx2 v[164:165], v[154:155], off offset:512
	global_load_dwordx2 v[160:161], v[154:155], off offset:640
	global_load_dwordx2 v[158:159], v[152:153], off offset:2688
	v_addc_co_u32_e32 v227, vcc, 0, v69, vcc
	v_add_co_u32_e32 v68, vcc, 0xcd60000, v68
	s_nop 1
	v_addc_co_u32_e32 v69, vcc, 0, v69, vcc
	global_load_dwordx2 v[154:155], v[226:227], off offset:2560
	global_load_dwordx2 v[156:157], v[68:69], off offset:512
	global_load_dwordx2 v[152:153], v[68:69], off offset:640
	s_nop 0
	global_load_dwordx2 v[68:69], v[226:227], off offset:2688
	s_waitcnt vmcnt(28)
	v_cvt_f32_ubyte1_e32 v233, v210
	v_cvt_f32_ubyte0_e32 v66, v220
	v_cvt_f32_ubyte0_e32 v232, v210
	v_cvt_f32_ubyte3_e32 v231, v210
	v_cvt_f32_ubyte2_e32 v230, v210
	v_rcp_iflag_f32_e32 v226, v66
	v_cvt_f32_ubyte1_e32 v66, v220
	v_rcp_iflag_f32_e32 v227, v66
	v_cvt_f32_ubyte2_e32 v66, v220
	v_rcp_iflag_f32_e32 v228, v66
	v_cvt_f32_ubyte3_e32 v66, v220
	v_rcp_iflag_f32_e32 v229, v66
	v_pk_mul_f32 v[226:227], v[226:227], v[232:233]
	v_cvt_f32_ubyte0_e32 v66, v221
	v_pk_mul_f32 v[130:131], v[130:131], v[226:227]
	v_rcp_iflag_f32_e32 v226, v66
	v_cvt_f32_ubyte1_e32 v66, v221
	v_rcp_iflag_f32_e32 v227, v66
	v_cvt_f32_ubyte2_e32 v66, v221
	v_pk_mul_f32 v[228:229], v[228:229], v[230:231]
	v_rcp_iflag_f32_e32 v220, v66
	v_cvt_f32_ubyte3_e32 v66, v221
	v_cvt_f32_ubyte1_e32 v231, v211
	v_cvt_f32_ubyte0_e32 v230, v211
	v_pk_mul_f32 v[132:133], v[132:133], v[228:229]
	v_rcp_iflag_f32_e32 v221, v66
	v_cvt_f32_ubyte3_e32 v229, v211
	v_cvt_f32_ubyte2_e32 v228, v211
	v_pk_mul_f32 v[210:211], v[226:227], v[230:231]
	v_cvt_f32_ubyte0_e32 v66, v222
	v_pk_mul_f32 v[126:127], v[126:127], v[210:211]
	v_rcp_iflag_f32_e32 v210, v66
	v_cvt_f32_ubyte1_e32 v66, v222
	v_rcp_iflag_f32_e32 v211, v66
	v_pk_mul_f32 v[220:221], v[220:221], v[228:229]
	v_cvt_f32_ubyte2_e32 v66, v222
	v_pk_mul_f32 v[128:129], v[128:129], v[220:221]
	v_rcp_iflag_f32_e32 v220, v66
	v_cvt_f32_ubyte3_e32 v66, v222
	v_cvt_f32_ubyte1_e32 v229, v224
	v_cvt_f32_ubyte0_e32 v228, v224
	v_rcp_iflag_f32_e32 v221, v66
	v_pk_mul_f32 v[210:211], v[210:211], v[228:229]
	v_cvt_f32_ubyte0_e32 v66, v223
	v_pk_mul_f32 v[122:123], v[122:123], v[210:211]
	v_rcp_iflag_f32_e32 v210, v66
	v_cvt_f32_ubyte1_e32 v66, v223
	v_rcp_iflag_f32_e32 v211, v66
	v_cvt_f32_ubyte3_e32 v227, v224
	v_cvt_f32_ubyte2_e32 v226, v224
	v_pk_mul_f32 v[220:221], v[220:221], v[226:227]
	v_cvt_f32_ubyte2_e32 v66, v223
	v_pk_mul_f32 v[124:125], v[124:125], v[220:221]
	v_rcp_iflag_f32_e32 v220, v66
	v_cvt_f32_ubyte3_e32 v66, v223
	v_cvt_f32_ubyte1_e32 v227, v225
	v_cvt_f32_ubyte0_e32 v226, v225
	v_rcp_iflag_f32_e32 v221, v66
	v_pk_mul_f32 v[210:211], v[210:211], v[226:227]
	s_waitcnt vmcnt(26)
	v_cvt_f32_ubyte0_e32 v66, v204
	v_pk_mul_f32 v[118:119], v[118:119], v[210:211]
	v_rcp_iflag_f32_e32 v210, v66
	v_cvt_f32_ubyte1_e32 v66, v204
	v_rcp_iflag_f32_e32 v211, v66
	v_cvt_f32_ubyte3_e32 v223, v225
	v_cvt_f32_ubyte2_e32 v222, v225
	v_pk_mul_f32 v[220:221], v[220:221], v[222:223]
	v_cvt_f32_ubyte2_e32 v66, v204
	v_pk_mul_f32 v[120:121], v[120:121], v[220:221]
	v_rcp_iflag_f32_e32 v220, v66
	v_cvt_f32_ubyte3_e32 v66, v204
	v_cvt_f32_ubyte1_e32 v225, v202
	v_cvt_f32_ubyte0_e32 v224, v202
	v_rcp_iflag_f32_e32 v221, v66
	v_pk_mul_f32 v[210:211], v[210:211], v[224:225]
	v_cvt_f32_ubyte0_e32 v66, v205
	v_pk_mul_f32 v[114:115], v[114:115], v[210:211]
	v_rcp_iflag_f32_e32 v210, v66
	v_cvt_f32_ubyte1_e32 v66, v205
	v_rcp_iflag_f32_e32 v211, v66
	v_cvt_f32_ubyte3_e32 v223, v202
	v_cvt_f32_ubyte2_e32 v222, v202
	v_cvt_f32_ubyte2_e32 v66, v205
	v_pk_mul_f32 v[220:221], v[220:221], v[222:223]
	v_rcp_iflag_f32_e32 v204, v66
	v_cvt_f32_ubyte3_e32 v66, v205
	v_cvt_f32_ubyte1_e32 v223, v203
	v_cvt_f32_ubyte0_e32 v222, v203
	v_pk_mul_f32 v[116:117], v[116:117], v[220:221]
	v_rcp_iflag_f32_e32 v205, v66
	v_cvt_f32_ubyte3_e32 v221, v203
	v_cvt_f32_ubyte2_e32 v220, v203
	v_pk_mul_f32 v[202:203], v[210:211], v[222:223]
	s_waitcnt vmcnt(25)
	v_cvt_f32_ubyte0_e32 v66, v200
	v_pk_mul_f32 v[110:111], v[110:111], v[202:203]
	v_rcp_iflag_f32_e32 v202, v66
	v_cvt_f32_ubyte1_e32 v66, v200
	v_rcp_iflag_f32_e32 v203, v66
	v_pk_mul_f32 v[204:205], v[204:205], v[220:221]
	v_cvt_f32_ubyte2_e32 v66, v200
	v_pk_mul_f32 v[112:113], v[112:113], v[204:205]
	v_rcp_iflag_f32_e32 v204, v66
	v_cvt_f32_ubyte3_e32 v66, v200
	s_waitcnt vmcnt(24)
; __device__ __forceinline__ float gate_v(unsigned q) { return (float)q; }
;     __device__ __forceinline__ void mid(f32x4 (&acc)[2][2][4][2], const Unit& u, int seg, int wr, int wc, int fr, int fq) const {
;     ...
;         for (int ai = 0; ai < 2; ++ai)
; #pragma unroll
;             for (int m = 0; m < 4; ++m)
; #pragma unroll
;                 for (int bj = 0; bj < 2; ++bj)
; #pragma unroll
;                     for (int e = 0; e < 8; ++e) { const unsigned a = (ga[ai][m][bj][e >> 2] >> (8 * (e & 3))) & 255u, b = (gb[ai][m][bj][e >> 2] >> (8 * (e & 3))) & 255u;
;                         acc[ai][bj][m][e >> 2][e & 3] *= gate_v(a) * __builtin_amdgcn_rcpf(gate_v(b)); }
	v_cvt_f32_ubyte1_e32 v221, v198
	v_cvt_f32_ubyte0_e32 v220, v198
	v_rcp_iflag_f32_e32 v205, v66
	v_pk_mul_f32 v[202:203], v[202:203], v[220:221]
	v_cvt_f32_ubyte0_e32 v66, v201
	v_pk_mul_f32 v[106:107], v[106:107], v[202:203]
	v_rcp_iflag_f32_e32 v202, v66
	v_cvt_f32_ubyte1_e32 v66, v201
	v_rcp_iflag_f32_e32 v203, v66
	v_cvt_f32_ubyte3_e32 v211, v198
	v_cvt_f32_ubyte2_e32 v210, v198
	v_cvt_f32_ubyte2_e32 v66, v201
	v_pk_mul_f32 v[204:205], v[204:205], v[210:211]
	v_rcp_iflag_f32_e32 v200, v66
	v_cvt_f32_ubyte3_e32 v66, v201
	v_cvt_f32_ubyte1_e32 v211, v199
	v_cvt_f32_ubyte0_e32 v210, v199
	v_pk_mul_f32 v[108:109], v[108:109], v[204:205]
	v_rcp_iflag_f32_e32 v201, v66
	v_cvt_f32_ubyte3_e32 v205, v199
	v_cvt_f32_ubyte2_e32 v204, v199
	v_pk_mul_f32 v[198:199], v[202:203], v[210:211]
	s_waitcnt vmcnt(22)
	v_cvt_f32_ubyte0_e32 v66, v196
	v_pk_mul_f32 v[102:103], v[102:103], v[198:199]
	v_rcp_iflag_f32_e32 v198, v66
	v_cvt_f32_ubyte1_e32 v66, v196
	v_rcp_iflag_f32_e32 v199, v66
	v_pk_mul_f32 v[200:201], v[200:201], v[204:205]
	v_cvt_f32_ubyte2_e32 v66, v196
	v_pk_mul_f32 v[104:105], v[104:105], v[200:201]
	v_rcp_iflag_f32_e32 v200, v66
	v_cvt_f32_ubyte3_e32 v66, v196
	v_cvt_f32_ubyte1_e32 v205, v194
	v_cvt_f32_ubyte0_e32 v204, v194
	v_rcp_iflag_f32_e32 v201, v66
	v_pk_mul_f32 v[198:199], v[198:199], v[204:205]
	v_cvt_f32_ubyte0_e32 v66, v197
	v_pk_mul_f32 v[98:99], v[98:99], v[198:199]
	v_rcp_iflag_f32_e32 v198, v66
	v_cvt_f32_ubyte1_e32 v66, v197
	v_rcp_iflag_f32_e32 v199, v66
	v_cvt_f32_ubyte3_e32 v203, v194
	v_cvt_f32_ubyte2_e32 v202, v194
	v_cvt_f32_ubyte2_e32 v66, v197
	v_pk_mul_f32 v[200:201], v[200:201], v[202:203]
	v_rcp_iflag_f32_e32 v196, v66
	v_cvt_f32_ubyte3_e32 v66, v197
	v_cvt_f32_ubyte1_e32 v203, v195
	v_cvt_f32_ubyte0_e32 v202, v195
	v_pk_mul_f32 v[100:101], v[100:101], v[200:201]
	v_rcp_iflag_f32_e32 v197, v66
	v_cvt_f32_ubyte3_e32 v201, v195
	v_cvt_f32_ubyte2_e32 v200, v195
	v_pk_mul_f32 v[194:195], v[198:199], v[202:203]
	s_waitcnt vmcnt(21)
	v_cvt_f32_ubyte0_e32 v66, v192
	v_pk_mul_f32 v[94:95], v[94:95], v[194:195]
	v_rcp_iflag_f32_e32 v194, v66
	v_cvt_f32_ubyte1_e32 v66, v192
	v_rcp_iflag_f32_e32 v195, v66
	v_pk_mul_f32 v[196:197], v[196:197], v[200:201]
	v_cvt_f32_ubyte2_e32 v66, v192
	v_pk_mul_f32 v[96:97], v[96:97], v[196:197]
	v_rcp_iflag_f32_e32 v196, v66
	v_cvt_f32_ubyte3_e32 v66, v192
	s_waitcnt vmcnt(20)
	v_cvt_f32_ubyte1_e32 v201, v190
	v_cvt_f32_ubyte0_e32 v200, v190
	v_rcp_iflag_f32_e32 v197, v66
	v_pk_mul_f32 v[194:195], v[194:195], v[200:201]
	v_cvt_f32_ubyte0_e32 v66, v193
	v_pk_mul_f32 v[90:91], v[90:91], v[194:195]
	v_rcp_iflag_f32_e32 v194, v66
	v_cvt_f32_ubyte1_e32 v66, v193
	v_rcp_iflag_f32_e32 v195, v66
	v_cvt_f32_ubyte3_e32 v199, v190
	v_cvt_f32_ubyte2_e32 v198, v190
	v_cvt_f32_ubyte2_e32 v66, v193
	v_pk_mul_f32 v[196:197], v[196:197], v[198:199]
	v_rcp_iflag_f32_e32 v192, v66
	v_cvt_f32_ubyte3_e32 v66, v193
	v_cvt_f32_ubyte1_e32 v199, v191
	v_cvt_f32_ubyte0_e32 v198, v191
	v_pk_mul_f32 v[92:93], v[92:93], v[196:197]
	v_rcp_iflag_f32_e32 v193, v66
	v_cvt_f32_ubyte3_e32 v197, v191
	v_cvt_f32_ubyte2_e32 v196, v191
	v_pk_mul_f32 v[190:191], v[194:195], v[198:199]
	s_waitcnt vmcnt(18)
	v_cvt_f32_ubyte0_e32 v66, v188
	v_pk_mul_f32 v[86:87], v[86:87], v[190:191]
	v_rcp_iflag_f32_e32 v190, v66
	v_cvt_f32_ubyte1_e32 v66, v188
	v_rcp_iflag_f32_e32 v191, v66
	v_pk_mul_f32 v[192:193], v[192:193], v[196:197]
	v_cvt_f32_ubyte2_e32 v66, v188
	v_pk_mul_f32 v[88:89], v[88:89], v[192:193]
	v_rcp_iflag_f32_e32 v192, v66
	v_cvt_f32_ubyte3_e32 v66, v188
	v_cvt_f32_ubyte1_e32 v197, v186
	v_cvt_f32_ubyte0_e32 v196, v186
	v_rcp_iflag_f32_e32 v193, v66
	v_pk_mul_f32 v[190:191], v[190:191], v[196:197]
	v_cvt_f32_ubyte0_e32 v66, v189
	v_pk_mul_f32 v[82:83], v[82:83], v[190:191]
	v_rcp_iflag_f32_e32 v190, v66
	v_cvt_f32_ubyte1_e32 v66, v189
	v_rcp_iflag_f32_e32 v191, v66
	v_cvt_f32_ubyte3_e32 v195, v186
	v_cvt_f32_ubyte2_e32 v194, v186
	v_cvt_f32_ubyte2_e32 v66, v189
	v_pk_mul_f32 v[192:193], v[192:193], v[194:195]
	v_rcp_iflag_f32_e32 v188, v66
	v_cvt_f32_ubyte3_e32 v66, v189
	v_cvt_f32_ubyte1_e32 v195, v187
	v_cvt_f32_ubyte0_e32 v194, v187
	v_pk_mul_f32 v[84:85], v[84:85], v[192:193]
	v_rcp_iflag_f32_e32 v189, v66
	v_cvt_f32_ubyte3_e32 v193, v187
	v_cvt_f32_ubyte2_e32 v192, v187
	v_pk_mul_f32 v[186:187], v[190:191], v[194:195]
	s_waitcnt vmcnt(17)
	v_cvt_f32_ubyte0_e32 v66, v184
	v_pk_mul_f32 v[78:79], v[78:79], v[186:187]
	v_rcp_iflag_f32_e32 v186, v66
	v_cvt_f32_ubyte1_e32 v66, v184
	v_rcp_iflag_f32_e32 v187, v66
	v_pk_mul_f32 v[188:189], v[188:189], v[192:193]
	v_cvt_f32_ubyte2_e32 v66, v184
	v_pk_mul_f32 v[80:81], v[80:81], v[188:189]
	v_rcp_iflag_f32_e32 v188, v66
	v_cvt_f32_ubyte3_e32 v66, v184
	s_waitcnt vmcnt(16)
	v_cvt_f32_ubyte1_e32 v193, v182
	v_cvt_f32_ubyte0_e32 v192, v182
	v_rcp_iflag_f32_e32 v189, v66
	v_pk_mul_f32 v[186:187], v[186:187], v[192:193]
	v_cvt_f32_ubyte0_e32 v66, v185
	v_pk_mul_f32 v[74:75], v[74:75], v[186:187]
	v_rcp_iflag_f32_e32 v186, v66
	v_cvt_f32_ubyte1_e32 v66, v185
	v_rcp_iflag_f32_e32 v187, v66
	v_cvt_f32_ubyte3_e32 v191, v182
	v_cvt_f32_ubyte2_e32 v190, v182
	v_cvt_f32_ubyte2_e32 v66, v185
	v_pk_mul_f32 v[188:189], v[188:189], v[190:191]
	v_rcp_iflag_f32_e32 v184, v66
	v_cvt_f32_ubyte3_e32 v66, v185
	v_cvt_f32_ubyte1_e32 v191, v183
	v_cvt_f32_ubyte0_e32 v190, v183
	v_pk_mul_f32 v[76:77], v[76:77], v[188:189]
	v_rcp_iflag_f32_e32 v185, v66
	v_cvt_f32_ubyte3_e32 v189, v183
	v_cvt_f32_ubyte2_e32 v188, v183
	v_pk_mul_f32 v[182:183], v[186:187], v[190:191]
	s_waitcnt vmcnt(14)
; __device__ __forceinline__ float gate_v(unsigned q) { return (float)q; }
;     __device__ __forceinline__ void mid(f32x4 (&acc)[2][2][4][2], const Unit& u, int seg, int wr, int wc, int fr, int fq) const {
;     ...
;         for (int ai = 0; ai < 2; ++ai)
; #pragma unroll
;             for (int m = 0; m < 4; ++m)
; #pragma unroll
;                 for (int bj = 0; bj < 2; ++bj)
; #pragma unroll
;                     for (int e = 0; e < 8; ++e) { const unsigned a = (ga[ai][m][bj][e >> 2] >> (8 * (e & 3))) & 255u, b = (gb[ai][m][bj][e >> 2] >> (8 * (e & 3))) & 255u;
;                         acc[ai][bj][m][e >> 2][e & 3] *= gate_v(a) * __builtin_amdgcn_rcpf(gate_v(b)); }
	v_cvt_f32_ubyte0_e32 v66, v180
	v_pk_mul_f32 v[70:71], v[70:71], v[182:183]
	v_rcp_iflag_f32_e32 v182, v66
	v_cvt_f32_ubyte1_e32 v66, v180
	v_rcp_iflag_f32_e32 v183, v66
	v_pk_mul_f32 v[184:185], v[184:185], v[188:189]
	v_cvt_f32_ubyte2_e32 v66, v180
	v_pk_mul_f32 v[72:73], v[72:73], v[184:185]
	v_rcp_iflag_f32_e32 v184, v66
	v_cvt_f32_ubyte3_e32 v66, v180
	v_cvt_f32_ubyte1_e32 v189, v178
	v_cvt_f32_ubyte0_e32 v188, v178
	v_rcp_iflag_f32_e32 v185, v66
	v_pk_mul_f32 v[182:183], v[182:183], v[188:189]
	v_cvt_f32_ubyte0_e32 v66, v181
	v_pk_mul_f32 v[62:63], v[62:63], v[182:183]
	v_rcp_iflag_f32_e32 v182, v66
	v_cvt_f32_ubyte1_e32 v66, v181
	v_rcp_iflag_f32_e32 v183, v66
	v_cvt_f32_ubyte3_e32 v187, v178
	v_cvt_f32_ubyte2_e32 v186, v178
	v_cvt_f32_ubyte2_e32 v66, v181
	v_pk_mul_f32 v[184:185], v[184:185], v[186:187]
	v_rcp_iflag_f32_e32 v180, v66
	v_cvt_f32_ubyte3_e32 v66, v181
	v_cvt_f32_ubyte1_e32 v187, v179
	v_cvt_f32_ubyte0_e32 v186, v179
	v_pk_mul_f32 v[64:65], v[64:65], v[184:185]
	v_rcp_iflag_f32_e32 v181, v66
	v_cvt_f32_ubyte3_e32 v185, v179
	v_cvt_f32_ubyte2_e32 v184, v179
	v_pk_mul_f32 v[178:179], v[182:183], v[186:187]
	s_waitcnt vmcnt(13)
	v_cvt_f32_ubyte0_e32 v66, v176
	v_pk_mul_f32 v[58:59], v[58:59], v[178:179]
	v_rcp_iflag_f32_e32 v178, v66
	v_cvt_f32_ubyte1_e32 v66, v176
	v_rcp_iflag_f32_e32 v179, v66
	v_pk_mul_f32 v[180:181], v[180:181], v[184:185]
	v_cvt_f32_ubyte2_e32 v66, v176
	v_pk_mul_f32 v[60:61], v[60:61], v[180:181]
	v_rcp_iflag_f32_e32 v180, v66
	v_cvt_f32_ubyte3_e32 v66, v176
	s_waitcnt vmcnt(12)
	v_cvt_f32_ubyte1_e32 v185, v174
	v_cvt_f32_ubyte0_e32 v184, v174
	v_rcp_iflag_f32_e32 v181, v66
	v_pk_mul_f32 v[178:179], v[178:179], v[184:185]
	v_cvt_f32_ubyte0_e32 v66, v177
	v_pk_mul_f32 v[54:55], v[54:55], v[178:179]
	v_rcp_iflag_f32_e32 v178, v66
	v_cvt_f32_ubyte1_e32 v66, v177
	v_rcp_iflag_f32_e32 v179, v66
	v_cvt_f32_ubyte3_e32 v183, v174
	v_cvt_f32_ubyte2_e32 v182, v174
	v_cvt_f32_ubyte2_e32 v66, v177
	v_pk_mul_f32 v[180:181], v[180:181], v[182:183]
	v_rcp_iflag_f32_e32 v176, v66
	v_cvt_f32_ubyte3_e32 v66, v177
	v_cvt_f32_ubyte1_e32 v183, v175
	v_cvt_f32_ubyte0_e32 v182, v175
	v_pk_mul_f32 v[56:57], v[56:57], v[180:181]
	v_rcp_iflag_f32_e32 v177, v66
	v_cvt_f32_ubyte3_e32 v181, v175
	v_cvt_f32_ubyte2_e32 v180, v175
	v_pk_mul_f32 v[174:175], v[178:179], v[182:183]
	s_waitcnt vmcnt(10)
	v_cvt_f32_ubyte0_e32 v66, v172
	v_pk_mul_f32 v[50:51], v[50:51], v[174:175]
	v_rcp_iflag_f32_e32 v174, v66
	v_cvt_f32_ubyte1_e32 v66, v172
	v_rcp_iflag_f32_e32 v175, v66
	v_pk_mul_f32 v[176:177], v[176:177], v[180:181]
	v_cvt_f32_ubyte2_e32 v66, v172
	v_pk_mul_f32 v[52:53], v[52:53], v[176:177]
	v_rcp_iflag_f32_e32 v176, v66
	v_cvt_f32_ubyte3_e32 v66, v172
	v_cvt_f32_ubyte1_e32 v181, v170
	v_cvt_f32_ubyte0_e32 v180, v170
	v_rcp_iflag_f32_e32 v177, v66
	v_pk_mul_f32 v[174:175], v[174:175], v[180:181]
	v_cvt_f32_ubyte0_e32 v66, v173
	v_pk_mul_f32 v[46:47], v[46:47], v[174:175]
	v_rcp_iflag_f32_e32 v174, v66
	v_cvt_f32_ubyte1_e32 v66, v173
	v_rcp_iflag_f32_e32 v175, v66
	v_cvt_f32_ubyte3_e32 v179, v170
	v_cvt_f32_ubyte2_e32 v178, v170
	v_cvt_f32_ubyte2_e32 v66, v173
	v_pk_mul_f32 v[176:177], v[176:177], v[178:179]
	v_rcp_iflag_f32_e32 v172, v66
	v_cvt_f32_ubyte3_e32 v66, v173
	v_cvt_f32_ubyte1_e32 v179, v171
	v_cvt_f32_ubyte0_e32 v178, v171
	v_pk_mul_f32 v[48:49], v[48:49], v[176:177]
	v_rcp_iflag_f32_e32 v173, v66
	v_cvt_f32_ubyte3_e32 v177, v171
	v_cvt_f32_ubyte2_e32 v176, v171
	v_pk_mul_f32 v[170:171], v[174:175], v[178:179]
	s_waitcnt vmcnt(9)
	v_cvt_f32_ubyte0_e32 v66, v168
	v_pk_mul_f32 v[42:43], v[42:43], v[170:171]
	v_rcp_iflag_f32_e32 v170, v66
	v_cvt_f32_ubyte1_e32 v66, v168
	v_rcp_iflag_f32_e32 v171, v66
	v_pk_mul_f32 v[172:173], v[172:173], v[176:177]
	v_cvt_f32_ubyte2_e32 v66, v168
	v_pk_mul_f32 v[44:45], v[44:45], v[172:173]
	v_rcp_iflag_f32_e32 v172, v66
	v_cvt_f32_ubyte3_e32 v66, v168
	s_waitcnt vmcnt(8)
	v_cvt_f32_ubyte1_e32 v177, v166
	v_cvt_f32_ubyte0_e32 v176, v166
	v_rcp_iflag_f32_e32 v173, v66
	v_pk_mul_f32 v[170:171], v[170:171], v[176:177]
	v_cvt_f32_ubyte0_e32 v66, v169
	v_pk_mul_f32 v[38:39], v[38:39], v[170:171]
	v_rcp_iflag_f32_e32 v170, v66
	v_cvt_f32_ubyte1_e32 v66, v169
	v_rcp_iflag_f32_e32 v171, v66
	v_cvt_f32_ubyte3_e32 v175, v166
	v_cvt_f32_ubyte2_e32 v174, v166
	v_cvt_f32_ubyte2_e32 v66, v169
	v_pk_mul_f32 v[172:173], v[172:173], v[174:175]
	v_rcp_iflag_f32_e32 v168, v66
	v_cvt_f32_ubyte3_e32 v66, v169
	v_cvt_f32_ubyte1_e32 v175, v167
	v_cvt_f32_ubyte0_e32 v174, v167
	v_pk_mul_f32 v[40:41], v[40:41], v[172:173]
	v_rcp_iflag_f32_e32 v169, v66
	v_cvt_f32_ubyte3_e32 v173, v167
	v_cvt_f32_ubyte2_e32 v172, v167
	v_pk_mul_f32 v[166:167], v[170:171], v[174:175]
	s_waitcnt vmcnt(6)
; __device__ __forceinline__ float gate_v(unsigned q) { return (float)q; }
;     __device__ __forceinline__ void mid(f32x4 (&acc)[2][2][4][2], const Unit& u, int seg, int wr, int wc, int fr, int fq) const {
;     ...
;         for (int ai = 0; ai < 2; ++ai)
; #pragma unroll
;             for (int m = 0; m < 4; ++m)
; #pragma unroll
;                 for (int bj = 0; bj < 2; ++bj)
; #pragma unroll
;                     for (int e = 0; e < 8; ++e) { const unsigned a = (ga[ai][m][bj][e >> 2] >> (8 * (e & 3))) & 255u, b = (gb[ai][m][bj][e >> 2] >> (8 * (e & 3))) & 255u;
;                         acc[ai][bj][m][e >> 2][e & 3] *= gate_v(a) * __builtin_amdgcn_rcpf(gate_v(b)); }
	v_cvt_f32_ubyte0_e32 v66, v164
	v_pk_mul_f32 v[34:35], v[34:35], v[166:167]
	v_rcp_iflag_f32_e32 v166, v66
	v_cvt_f32_ubyte1_e32 v66, v164
	v_rcp_iflag_f32_e32 v167, v66
	v_pk_mul_f32 v[168:169], v[168:169], v[172:173]
	v_cvt_f32_ubyte2_e32 v66, v164
	v_pk_mul_f32 v[36:37], v[36:37], v[168:169]
	v_rcp_iflag_f32_e32 v168, v66
	v_cvt_f32_ubyte3_e32 v66, v164
	v_cvt_f32_ubyte1_e32 v173, v162
	v_cvt_f32_ubyte0_e32 v172, v162
	v_rcp_iflag_f32_e32 v169, v66
	v_pk_mul_f32 v[166:167], v[166:167], v[172:173]
	v_cvt_f32_ubyte0_e32 v66, v165
	v_pk_mul_f32 v[30:31], v[30:31], v[166:167]
	v_rcp_iflag_f32_e32 v166, v66
	v_cvt_f32_ubyte1_e32 v66, v165
	v_rcp_iflag_f32_e32 v167, v66
	v_cvt_f32_ubyte3_e32 v171, v162
	v_cvt_f32_ubyte2_e32 v170, v162
	v_cvt_f32_ubyte2_e32 v66, v165
	v_pk_mul_f32 v[168:169], v[168:169], v[170:171]
	v_rcp_iflag_f32_e32 v164, v66
	v_cvt_f32_ubyte3_e32 v66, v165
	v_cvt_f32_ubyte1_e32 v171, v163
	v_cvt_f32_ubyte0_e32 v170, v163
	v_pk_mul_f32 v[32:33], v[32:33], v[168:169]
	v_rcp_iflag_f32_e32 v165, v66
	v_cvt_f32_ubyte3_e32 v169, v163
	v_cvt_f32_ubyte2_e32 v168, v163
	v_pk_mul_f32 v[162:163], v[166:167], v[170:171]
	s_waitcnt vmcnt(5)
	v_cvt_f32_ubyte0_e32 v66, v160
	v_pk_mul_f32 v[26:27], v[26:27], v[162:163]
	v_rcp_iflag_f32_e32 v162, v66
	v_cvt_f32_ubyte1_e32 v66, v160
	v_rcp_iflag_f32_e32 v163, v66
	v_pk_mul_f32 v[164:165], v[164:165], v[168:169]
	v_cvt_f32_ubyte2_e32 v66, v160
	v_pk_mul_f32 v[28:29], v[28:29], v[164:165]
	v_rcp_iflag_f32_e32 v164, v66
	v_cvt_f32_ubyte3_e32 v66, v160
	s_waitcnt vmcnt(4)
	v_cvt_f32_ubyte1_e32 v169, v158
	v_cvt_f32_ubyte0_e32 v168, v158
	v_rcp_iflag_f32_e32 v165, v66
	v_pk_mul_f32 v[162:163], v[162:163], v[168:169]
	v_cvt_f32_ubyte0_e32 v66, v161
	v_pk_mul_f32 v[22:23], v[22:23], v[162:163]
	v_rcp_iflag_f32_e32 v162, v66
	v_cvt_f32_ubyte1_e32 v66, v161
	v_rcp_iflag_f32_e32 v163, v66
	v_cvt_f32_ubyte3_e32 v167, v158
	v_cvt_f32_ubyte2_e32 v166, v158
	v_cvt_f32_ubyte2_e32 v66, v161
	v_pk_mul_f32 v[164:165], v[164:165], v[166:167]
	v_rcp_iflag_f32_e32 v160, v66
	v_cvt_f32_ubyte3_e32 v66, v161
	v_cvt_f32_ubyte1_e32 v167, v159
	v_cvt_f32_ubyte0_e32 v166, v159
	v_pk_mul_f32 v[24:25], v[24:25], v[164:165]
	v_rcp_iflag_f32_e32 v161, v66
	v_cvt_f32_ubyte3_e32 v165, v159
	v_cvt_f32_ubyte2_e32 v164, v159
	v_pk_mul_f32 v[158:159], v[162:163], v[166:167]
	s_waitcnt vmcnt(2)
	v_cvt_f32_ubyte0_e32 v66, v156
	v_pk_mul_f32 v[18:19], v[18:19], v[158:159]
	v_rcp_iflag_f32_e32 v158, v66
	v_cvt_f32_ubyte1_e32 v66, v156
	v_rcp_iflag_f32_e32 v159, v66
	v_pk_mul_f32 v[160:161], v[160:161], v[164:165]
	v_cvt_f32_ubyte2_e32 v66, v156
	v_pk_mul_f32 v[20:21], v[20:21], v[160:161]
	v_rcp_iflag_f32_e32 v160, v66
	v_cvt_f32_ubyte3_e32 v66, v156
	v_cvt_f32_ubyte1_e32 v165, v154
	v_cvt_f32_ubyte0_e32 v164, v154
	v_rcp_iflag_f32_e32 v161, v66
	v_pk_mul_f32 v[158:159], v[158:159], v[164:165]
	v_cvt_f32_ubyte0_e32 v66, v157
	v_pk_mul_f32 v[14:15], v[14:15], v[158:159]
	v_rcp_iflag_f32_e32 v158, v66
	v_cvt_f32_ubyte1_e32 v66, v157
	v_rcp_iflag_f32_e32 v159, v66
	v_cvt_f32_ubyte3_e32 v163, v154
	v_cvt_f32_ubyte2_e32 v162, v154
	v_cvt_f32_ubyte2_e32 v66, v157
	v_pk_mul_f32 v[160:161], v[160:161], v[162:163]
	v_rcp_iflag_f32_e32 v156, v66
	v_cvt_f32_ubyte3_e32 v66, v157
	v_cvt_f32_ubyte1_e32 v163, v155
	v_cvt_f32_ubyte0_e32 v162, v155
	v_pk_mul_f32 v[16:17], v[16:17], v[160:161]
	v_rcp_iflag_f32_e32 v157, v66
	v_cvt_f32_ubyte3_e32 v161, v155
	v_cvt_f32_ubyte2_e32 v160, v155
	v_pk_mul_f32 v[154:155], v[158:159], v[162:163]
	s_waitcnt vmcnt(1)
	v_cvt_f32_ubyte0_e32 v66, v152
	v_pk_mul_f32 v[10:11], v[10:11], v[154:155]
	v_rcp_iflag_f32_e32 v154, v66
	v_cvt_f32_ubyte1_e32 v66, v152
	v_rcp_iflag_f32_e32 v155, v66
	v_pk_mul_f32 v[156:157], v[156:157], v[160:161]
	v_cvt_f32_ubyte2_e32 v66, v152
	v_pk_mul_f32 v[12:13], v[12:13], v[156:157]
	v_rcp_iflag_f32_e32 v156, v66
	v_cvt_f32_ubyte3_e32 v66, v152
	s_waitcnt vmcnt(0)
	v_cvt_f32_ubyte1_e32 v161, v68
	v_cvt_f32_ubyte0_e32 v160, v68
	v_rcp_iflag_f32_e32 v157, v66
	v_pk_mul_f32 v[154:155], v[154:155], v[160:161]
	v_cvt_f32_ubyte0_e32 v66, v153
	v_pk_mul_f32 v[6:7], v[6:7], v[154:155]
	v_rcp_iflag_f32_e32 v154, v66
	v_cvt_f32_ubyte1_e32 v66, v153
	v_rcp_iflag_f32_e32 v155, v66
	v_cvt_f32_ubyte2_e32 v66, v153
	v_rcp_iflag_f32_e32 v152, v66
	v_cvt_f32_ubyte3_e32 v66, v153
	v_rcp_iflag_f32_e32 v153, v66
	v_cvt_f32_ubyte3_e32 v159, v68
	v_cvt_f32_ubyte2_e32 v158, v68
	v_pk_mul_f32 v[156:157], v[156:157], v[158:159]
	v_cvt_f32_ubyte1_e32 v159, v69
	v_pk_mul_f32 v[8:9], v[8:9], v[156:157]
	v_cvt_f32_ubyte3_e32 v157, v69
	v_cvt_f32_ubyte2_e32 v156, v69
	v_cvt_f32_ubyte0_e32 v158, v69
	v_pk_mul_f32 v[68:69], v[154:155], v[158:159]
	v_pk_mul_f32 v[152:153], v[152:153], v[156:157]
	v_pk_mul_f32 v[2:3], v[2:3], v[68:69]
	v_pk_mul_f32 v[4:5], v[4:5], v[152:153]
	s_branch .LBB0_781

;     __host__ __device__ bool next(int i, Unit& u) const { if (i != 0 || r < 0 || r >= 148) return false; if (r < 116) { u.pm = r % 29; u.pn = 47 + r / 29; } else { u.pm = 32; u.pn = 19 + (r - 116); } u.ko = 0; return true; }
;     __host__ __device__ bool next(int i, Unit& u) const { const int L = i * G + (G - 1 - c); if (L >= nN * S) return false; u.pm = pm; u.pn = L % nN; u.ko = (L / nN) * ksub; return true; }
; template <class Epi, class Sched, bool ALIGN_EPI = false, bool SP2 = false>
; __device__ __forceinline__ void gemm_phase(PG8_LAS unsigned char* lds, const Gemm g, const Sched& S, const Epi& E) {
;     ...
;         const bool has_next = S.next(ui + 1, nxt);
;         const char* nA = has_next ? (const char*)g.A + (size_t)nxt.pm * tstep + (size_t)nxt.ko * 2 : cA; const char* nB = has_next ? (const char*)g.Bt + (size_t)nxt.pn * tstep + (size_t)nxt.ko * 2 : cB;
;     ...
; #pragma unroll
;         for (int a = 0; a < 2; ++a)
; #pragma unroll
;             for (int b = 0; b < 2; ++b)
; #pragma unroll
;                 for (int m = 0; m < 4; ++m)
; #pragma unroll
;                     for (int n = 0; n < 2; ++n) acc[a][b][m][n] = (f32x4){0.f, 0.f, 0.f, 0.f};
;         cur = nxt; cA = nA; cB = nB; ++ui;
.LBB0_1201:
	s_ashr_i32 s31, s30, 31
	s_lshl_b64 s[2:3], s[30:31], 20
	s_add_u32 s34, s64, s2
	s_addc_u32 s35, s65, s3
	s_and_b64 s[2:3], exec, s[12:13]
	s_cselect_b32 s1, s43, s35
	s_cselect_b32 s2, s42, s34
	s_ashr_i32 s29, s28, 31
	s_lshl_b64 s[36:37], s[28:29], 20
	s_add_u32 s36, s66, s36
	s_addc_u32 s37, s67, s37
	s_and_b64 s[46:47], exec, s[12:13]
	s_cselect_b32 s3, s45, s37
	s_cselect_b32 s29, s44, s36
	v_mov_b32_e32 v2, 0
	s_cmp_lg_u32 s30, 32
	s_mov_b32 s31, 0
	s_cselect_b64 s[46:47], -1, 0
	v_mov_b32_e32 v3, v2
	v_mov_b32_e32 v4, v2
	v_mov_b32_e32 v5, v2
	v_mov_b32_e32 v6, v2
	v_mov_b32_e32 v7, v2
	v_mov_b32_e32 v8, v2
	v_mov_b32_e32 v9, v2
	v_mov_b32_e32 v18, v2
	v_mov_b32_e32 v19, v2
	v_mov_b32_e32 v20, v2
	v_mov_b32_e32 v21, v2
	v_mov_b32_e32 v22, v2
	v_mov_b32_e32 v23, v2
	v_mov_b32_e32 v24, v2
	v_mov_b32_e32 v25, v2
	v_mov_b32_e32 v34, v2
	v_mov_b32_e32 v35, v2
	v_mov_b32_e32 v36, v2
	v_mov_b32_e32 v37, v2
	v_mov_b32_e32 v38, v2
	v_mov_b32_e32 v39, v2
	v_mov_b32_e32 v40, v2
	v_mov_b32_e32 v41, v2
	v_mov_b32_e32 v50, v2
	v_mov_b32_e32 v51, v2
	v_mov_b32_e32 v52, v2
	v_mov_b32_e32 v53, v2
	v_mov_b32_e32 v54, v2
	v_mov_b32_e32 v55, v2
	v_mov_b32_e32 v56, v2
	v_mov_b32_e32 v57, v2
	v_mov_b32_e32 v10, v2
	v_mov_b32_e32 v11, v2
	v_mov_b32_e32 v12, v2
	v_mov_b32_e32 v13, v2
	v_mov_b32_e32 v14, v2
	v_mov_b32_e32 v15, v2
	v_mov_b32_e32 v16, v2
	v_mov_b32_e32 v17, v2
	v_mov_b32_e32 v26, v2
	v_mov_b32_e32 v27, v2
	v_mov_b32_e32 v28, v2
	v_mov_b32_e32 v29, v2
	v_mov_b32_e32 v30, v2
	v_mov_b32_e32 v31, v2
	v_mov_b32_e32 v32, v2
	v_mov_b32_e32 v33, v2
	v_mov_b32_e32 v42, v2
	v_mov_b32_e32 v43, v2
	v_mov_b32_e32 v44, v2
	v_mov_b32_e32 v45, v2
	v_mov_b32_e32 v46, v2
	v_mov_b32_e32 v47, v2
	v_mov_b32_e32 v48, v2
	v_mov_b32_e32 v49, v2
	v_mov_b32_e32 v58, v2
	v_mov_b32_e32 v59, v2
	v_mov_b32_e32 v60, v2
	v_mov_b32_e32 v61, v2
	v_mov_b32_e32 v62, v2
	v_mov_b32_e32 v63, v2
	v_mov_b32_e32 v64, v2
	v_mov_b32_e32 v65, v2
	v_mov_b32_e32 v68, v2
	v_mov_b32_e32 v69, v2
	v_mov_b32_e32 v70, v2
	v_mov_b32_e32 v71, v2
	v_mov_b32_e32 v72, v2
	v_mov_b32_e32 v73, v2
	v_mov_b32_e32 v74, v2
	v_mov_b32_e32 v75, v2
	v_mov_b32_e32 v84, v2
	v_mov_b32_e32 v85, v2
	v_mov_b32_e32 v86, v2
	v_mov_b32_e32 v87, v2
	v_mov_b32_e32 v88, v2
	v_mov_b32_e32 v89, v2
	v_mov_b32_e32 v90, v2
	v_mov_b32_e32 v91, v2
	v_mov_b32_e32 v100, v2
	v_mov_b32_e32 v101, v2
	v_mov_b32_e32 v102, v2
	v_mov_b32_e32 v103, v2
	v_mov_b32_e32 v104, v2
	v_mov_b32_e32 v105, v2
	v_mov_b32_e32 v106, v2
	v_mov_b32_e32 v107, v2
	v_mov_b32_e32 v116, v2
	v_mov_b32_e32 v117, v2
	v_mov_b32_e32 v118, v2
	v_mov_b32_e32 v119, v2
	v_mov_b32_e32 v120, v2
	v_mov_b32_e32 v121, v2
	v_mov_b32_e32 v122, v2
	v_mov_b32_e32 v123, v2
	v_mov_b32_e32 v76, v2
	v_mov_b32_e32 v77, v2
	v_mov_b32_e32 v78, v2
	v_mov_b32_e32 v79, v2
	v_mov_b32_e32 v80, v2
	v_mov_b32_e32 v81, v2
	v_mov_b32_e32 v82, v2
	v_mov_b32_e32 v83, v2
	v_mov_b32_e32 v92, v2
	v_mov_b32_e32 v93, v2
	v_mov_b32_e32 v94, v2
	v_mov_b32_e32 v95, v2
	v_mov_b32_e32 v96, v2
	v_mov_b32_e32 v97, v2
	v_mov_b32_e32 v98, v2
	v_mov_b32_e32 v99, v2
	v_mov_b32_e32 v108, v2
	v_mov_b32_e32 v109, v2
	v_mov_b32_e32 v110, v2
	v_mov_b32_e32 v111, v2
	v_mov_b32_e32 v112, v2
	v_mov_b32_e32 v113, v2
	v_mov_b32_e32 v114, v2
	v_mov_b32_e32 v115, v2
	v_mov_b32_e32 v124, v2
	v_mov_b32_e32 v125, v2
	v_mov_b32_e32 v126, v2
	v_mov_b32_e32 v127, v2
	v_mov_b32_e32 v128, v2
	v_mov_b32_e32 v129, v2
	v_mov_b32_e32 v130, v2
	v_mov_b32_e32 v131, v2
	s_branch .LBB0_1206
